# residual epilogues (FF-out x2, out-proj): gamma of the lane's columns staged once per unit in a per-wave LDS slot instead of 32 global reloads serialized behind the X stores
# baseline (speedup 1.0000x reference)
;     template <int AI> __device__ __forceinline__ void half_rows(AccT acc, int row0, int col0, int slot, int sq, int fq, const f32x4 (&gsc)[4]) const {
;         v4u xw[4][2];
; #pragma unroll
;         for (int m = 0; m < 4; ++m)
; #pragma unroll
;             for (int bj = 0; bj < 2; ++bj) xw[m][bj] = *(const v4u*)(X + (size_t)(row0 + m * 16) * DM + col0 + bj * HALF);
; #pragma unroll
;         for (int m = 0; m < 4; ++m) { const int row = row0 + m * 16;
;             float ss = 0.f;
; #pragma unroll
;             for (int bj = 0; bj < 2; ++bj) { const size_t off = (size_t)row * DM + col0 + bj * HALF;
;                 float xi[8]; unpack8(xw[m][bj], xi);
;                 const f32x4 x0 = (f32x4){xi[0], xi[1], xi[2], xi[3]} + gsc[bj * 2] * acc[AI][bj][m][0], x1 = (f32x4){xi[4], xi[5], xi[6], xi[7]} + gsc[bj * 2 + 1] * acc[AI][bj][m][1];
;                 { u32x4 xs_; xs_.x = cvt_pk_bf16(x0[0], x0[1]); xs_.y = cvt_pk_bf16(x0[2], x0[3]); xs_.z = cvt_pk_bf16(x1[0], x1[1]); xs_.w = cvt_pk_bf16(x1[2], x1[3]); *(u32x4*)(X + off) = xs_; }
;                 if (NEXT) { ss += ((x0.x * x0.x + x0.y * x0.y) + (x0.z * x0.z + x0.w * x0.w)) + ((x1.x * x1.x + x1.y * x1.y) + (x1.z * x1.z + x1.w * x1.w));
;                     const float* gp_ = gam + (size_t)sq * DM + col0 + bj * HALF; const f32x4 y0 = x0 * *(const f32x4*)gp_, y1 = x1 * *(const f32x4*)(gp_ + 4);
;                     u32x4 w; w.x = cvt_pk_bf16(y0[0], y0[1]); w.y = cvt_pk_bf16(y0[2], y0[3]); w.z = cvt_pk_bf16(y1[0], y1[1]); w.w = cvt_pk_bf16(y1[2], y1[3]);
;                     *(u32x4*)(XB + off) = w; } }
;             if (NEXT) { ss += __shfl_xor(ss, 16); ss += __shfl_xor(ss, 32); if (fq == 0) SSQ[(size_t)row * 16 + slot] = ss; } }
;     }
;     __device__ __forceinline__ void operator()(AccT acc, const Unit& u, int wr, int wc, int fr, int fq) const {
;         const int upm = u.pm, upn = u.pn, uhalf = u.half;
;         const int col0 = upn * BM + wc * 32 + 8 * fq, sq = upm >> 3, slot = upn * 4 + wc, rbase = upm * BM + wr * 64 + fr;
;         f32x4 gsc[4];
; #pragma unroll
;         for (int q = 0; q < 4; ++q) gsc[q] = *(const f32x4*)(gate + (size_t)sq * NMOD + col0 + (q >> 1) * HALF + 4 * (q & 1)) * scale;
;         if (uhalf != 1) half_rows<0>(acc, rbase, col0, slot, sq, fq, gsc);
;         if (uhalf != 0) half_rows<1>(acc, rbase + HALF, col0, slot, sq, fq, gsc);
.LBB0_557:
	s_ashr_i32 s30, s64, 3
	v_lshl_or_b32 v170, s65, 8, v198
	s_lshl_b32 s34, s65, 2
	v_lshl_add_u32 v184, s64, 8, v1
	s_ashr_i32 s31, s30, 31
	s_mul_i32 s28, s30, 0x9000
	v_ashrrev_i32_e32 v171, 31, v170
	v_ashrrev_i32_e32 v185, 31, v184
	s_mul_hi_i32 s29, s30, 0x9000
	s_add_u32 s28, s14, s28
	v_lshl_add_u64 v[182:183], v[170:171], 1, s[0:1]
	v_lshlrev_b64 v[98:99], 11, v[184:185]
	s_addc_u32 s29, s15, s29
	v_lshlrev_b64 v[172:173], 2, v[170:171]
	v_lshl_add_u64 v[222:223], v[182:183], 0, v[98:99]
	v_lshl_add_u64 v[98:99], s[28:29], 0, v[172:173]
	global_load_dwordx4 v[174:177], v[222:223], off
	global_load_dwordx4 v[178:181], v[98:99], off
	global_load_dwordx4 v[206:209], v[98:99], off offset:16
	s_or_b32 s28, s34, s50
	v_or_b32_e32 v194, 16, v184
	v_or_b32_e32 v190, 32, v184
	v_or_b32_e32 v186, 48, v184
	s_lshl_b64 s[30:31], s[30:31], 12
	s_ashr_i32 s29, s28, 31
	v_ashrrev_i32_e32 v195, 31, v194
	v_ashrrev_i32_e32 v191, 31, v190
	v_ashrrev_i32_e32 v187, 31, v186
	s_add_u32 s30, s16, s30
	v_lshlrev_b64 v[100:101], 11, v[194:195]
	v_lshlrev_b64 v[110:111], 11, v[190:191]
	v_lshlrev_b64 v[112:113], 11, v[186:187]
	global_load_dwordx4 v[210:213], v[222:223], off offset:256
	s_addc_u32 s31, s17, s31
	v_lshl_add_u64 v[196:197], v[182:183], 0, v[100:101]
	v_lshl_add_u64 v[192:193], v[182:183], 0, v[110:111]
	v_lshl_add_u64 v[188:189], v[182:183], 0, v[112:113]
	global_load_dwordx4 v[214:217], v[98:99], off offset:528
	global_load_dwordx4 v[218:221], v[98:99], off offset:512
	global_load_dwordx4 v[150:153], v[196:197], off
	global_load_dwordx4 v[146:149], v[196:197], off offset:256
	global_load_dwordx4 v[134:137], v[192:193], off
	global_load_dwordx4 v[122:125], v[192:193], off offset:256
	global_load_dwordx4 v[110:113], v[188:189], off
	global_load_dwordx4 v[98:101], v[188:189], off offset:256
	v_lshl_add_u64 v[172:173], s[30:31], 0, v[172:173]
	global_load_dwordx4 v[244:247], v[172:173], off
	global_load_dwordx4 v[248:251], v[172:173], off offset:16
	v_lshrrev_b32_e32 v255, 6, v0
	v_lshlrev_b32_e32 v255, 8, v255
	v_bfe_u32 v252, v0, 4, 2
	v_lshl_add_u32 v255, v252, 6, v255
	v_add_u32_e32 v255, 0x20000, v255
	s_waitcnt vmcnt(0)
	ds_write_b128 v255, v[244:247]
	ds_write_b128 v255, v[248:251] offset:16
	global_load_dwordx4 v[244:247], v[172:173], off offset:512
	global_load_dwordx4 v[248:251], v[172:173], off offset:528
	s_waitcnt vmcnt(0)
	ds_write_b128 v255, v[244:247] offset:32
	ds_write_b128 v255, v[248:251] offset:48
	s_waitcnt lgkmcnt(0)
	v_lshlrev_b32_e32 v224, 16, v174
	v_and_b32_e32 v225, 0xffff0000, v174
	v_lshlrev_b32_e32 v226, 16, v175
	v_and_b32_e32 v227, 0xffff0000, v175
	v_lshlrev_b32_e32 v228, 16, v176
	v_and_b32_e32 v229, 0xffff0000, v176
	v_lshlrev_b32_e32 v230, 16, v177
	v_and_b32_e32 v231, 0xffff0000, v177
	v_pk_mul_f32 v[180:181], v[180:181], 0.5 op_sel_hi:[1,0]
	v_pk_mul_f32 v[178:179], v[178:179], 0.5 op_sel_hi:[1,0]
	v_pk_mul_f32 v[176:177], v[208:209], 0.5 op_sel_hi:[1,0]
	v_pk_mul_f32 v[174:175], v[206:207], 0.5 op_sel_hi:[1,0]
	v_pk_fma_f32 v[226:227], v[144:145], v[180:181], v[226:227]
	v_pk_fma_f32 v[232:233], v[142:143], v[178:179], v[224:225]
	v_pk_fma_f32 v[230:231], v[140:141], v[176:177], v[230:231]
	v_pk_fma_f32 v[228:229], v[138:139], v[174:175], v[228:229]
	v_cvt_pk_bf16_f32 v138, v232, v233
	v_cvt_pk_bf16_f32 v139, v226, v227
	v_lshlrev_b32_e32 v242, 16, v212
	v_cvt_pk_bf16_f32 v140, v228, v229
	v_cvt_pk_bf16_f32 v141, v230, v231
	global_store_dwordx4 v[222:223], v[138:141], off
	ds_read_b128 v[206:209], v255
	s_nop 0
	ds_read_b128 v[222:225], v255 offset:16
	v_lshlrev_b64 v[138:139], 10, v[184:185]
	v_lshl_add_u64 v[138:139], v[138:139], 0, v[170:171]
	v_lshlrev_b64 v[234:235], 1, v[138:139]
	v_and_b32_e32 v243, 0xffff0000, v212
	v_lshlrev_b32_e32 v212, 16, v213
	v_and_b32_e32 v213, 0xffff0000, v213
	v_pk_mul_f32 v[140:141], v[216:217], 0.5 op_sel_hi:[1,0]
	v_pk_mul_f32 v[138:139], v[214:215], 0.5 op_sel_hi:[1,0]
	v_lshl_add_u64 v[236:237], s[10:11], 0, v[234:235]
	v_or_b32_e32 v234, 0x100, v234
	v_lshlrev_b32_e32 v240, 16, v210
	v_and_b32_e32 v241, 0xffff0000, v210
	v_lshlrev_b32_e32 v210, 16, v211
	v_and_b32_e32 v211, 0xffff0000, v211
	v_pk_mul_f32 v[144:145], v[220:221], 0.5 op_sel_hi:[1,0]
	v_pk_mul_f32 v[142:143], v[218:219], 0.5 op_sel_hi:[1,0]
	v_pk_fma_f32 v[212:213], v[128:129], v[140:141], v[212:213]
	v_pk_fma_f32 v[216:217], v[126:127], v[138:139], v[242:243]
	v_lshl_add_u64 v[238:239], s[0:1], 0, v[234:235]
	v_pk_fma_f32 v[210:211], v[132:133], v[144:145], v[210:211]
	v_pk_fma_f32 v[214:215], v[130:131], v[142:143], v[240:241]
	v_mul_f32_e32 v205, v229, v229
	v_mul_f32_e32 v218, v231, v231
	v_mul_f32_e32 v219, v215, v215
	v_mul_f32_e32 v220, v211, v211
	v_mul_f32_e32 v221, v217, v217
	v_fmac_f32_e32 v205, v228, v228
	v_fmac_f32_e32 v218, v230, v230
	v_fmac_f32_e32 v219, v214, v214
	v_fmac_f32_e32 v220, v210, v210
	v_fmac_f32_e32 v221, v216, v216
	s_waitcnt lgkmcnt(0)
	v_pk_mul_f32 v[128:129], v[226:227], v[208:209]
	v_pk_mul_f32 v[126:127], v[232:233], v[206:207]
	s_waitcnt lgkmcnt(0)
	v_pk_mul_f32 v[130:131], v[230:231], v[224:225]
	v_pk_mul_f32 v[132:133], v[228:229], v[222:223]
	v_cvt_pk_bf16_f32 v126, v126, v127
	v_cvt_pk_bf16_f32 v127, v128, v129
	v_mul_f32_e32 v222, v213, v213
	v_cvt_pk_bf16_f32 v128, v132, v133
	v_cvt_pk_bf16_f32 v129, v130, v131
	global_store_dwordx4 v[236:237], v[126:129], off
	v_fmac_f32_e32 v222, v212, v212
	s_nop 0
	v_cvt_pk_bf16_f32 v126, v214, v215
	v_cvt_pk_bf16_f32 v127, v210, v211
	v_cvt_pk_bf16_f32 v128, v216, v217
	v_cvt_pk_bf16_f32 v129, v212, v213
	global_store_dwordx4 v[238:239], v[126:129], off
	ds_read_b128 v[130:133], v255 offset:32
	ds_read_b128 v[206:209], v255 offset:48
	v_and_b32_e32 v127, 64, v204
	v_mul_f32_e32 v128, v233, v233
	v_mul_f32_e32 v129, v227, v227
	v_xor_b32_e32 v126, 16, v204
	v_add_u32_e32 v127, 64, v127
	v_fmac_f32_e32 v128, v232, v232
	v_fmac_f32_e32 v129, v226, v226
	v_cmp_lt_i32_e32 vcc, v126, v127
	v_add_f32_e32 v128, v128, v129
	v_add_f32_e32 v129, v205, v218
	v_add_f32_e32 v205, v219, v220
	v_add_f32_e32 v218, v221, v222
	v_cndmask_b32_e32 v126, v204, v126, vcc
	v_add_f32_e32 v128, v128, v129
	v_add_f32_e32 v129, v205, v218
	v_lshlrev_b32_e32 v126, 2, v126
	v_add_f32_e32 v128, v128, v129
	ds_bpermute_b32 v129, v126, v128
	v_xor_b32_e32 v205, 32, v204
	v_cmp_lt_i32_e32 vcc, v205, v127
	s_waitcnt lgkmcnt(0)
	v_add_f32_e32 v128, v128, v129
	v_cndmask_b32_e32 v127, v204, v205, vcc
	v_lshlrev_b32_e32 v127, 2, v127
	ds_bpermute_b32 v129, v127, v128
	s_waitcnt lgkmcnt(0)
	v_pk_mul_f32 v[132:133], v[210:211], v[132:133]
	v_pk_mul_f32 v[130:131], v[214:215], v[130:131]
	s_waitcnt lgkmcnt(0)
	v_pk_mul_f32 v[206:207], v[216:217], v[206:207]
	v_cvt_pk_bf16_f32 v130, v130, v131
	v_cvt_pk_bf16_f32 v131, v132, v133
	v_pk_mul_f32 v[208:209], v[212:213], v[208:209]
	v_cvt_pk_bf16_f32 v132, v206, v207
	v_lshl_add_u64 v[206:207], s[10:11], 0, v[234:235]
	v_cvt_pk_bf16_f32 v133, v208, v209
	global_store_dwordx4 v[206:207], v[130:133], off
	s_and_saveexec_b64 s[30:31], s[4:5]
	s_cbranch_execz .LBB0_559
; __device__ __forceinline__ void unpack8(const v4u w, float (&o)[8]) { o[0] = bflo(w.x); o[1] = bfhi(w.x); o[2] = bflo(w.y); o[3] = bfhi(w.y); o[4] = bflo(w.z); o[5] = bfhi(w.z); o[6] = bflo(w.w); o[7] = bfhi(w.w); }
; __device__ __forceinline__ unsigned cvt_pk_bf16(float lo, float hi) { unsigned r; asm volatile("v_cvt_pk_bf16_f32 %0, %1, %2" : "=v"(r) : "v"(lo), "v"(hi)); return r; }
;     template <int AI> __device__ __forceinline__ void half_rows(AccT acc, int row0, int col0, int slot, int sq, int fq, const f32x4 (&gsc)[4]) const {
;     ...
;         for (int m = 0; m < 4; ++m) { const int row = row0 + m * 16;
;             float ss = 0.f;
; #pragma unroll
;             for (int bj = 0; bj < 2; ++bj) { const size_t off = (size_t)row * DM + col0 + bj * HALF;
;                 float xi[8]; unpack8(xw[m][bj], xi);
;                 const f32x4 x0 = (f32x4){xi[0], xi[1], xi[2], xi[3]} + gsc[bj * 2] * acc[AI][bj][m][0], x1 = (f32x4){xi[4], xi[5], xi[6], xi[7]} + gsc[bj * 2 + 1] * acc[AI][bj][m][1];
;                 { u32x4 xs_; xs_.x = cvt_pk_bf16(x0[0], x0[1]); xs_.y = cvt_pk_bf16(x0[2], x0[3]); xs_.z = cvt_pk_bf16(x1[0], x1[1]); xs_.w = cvt_pk_bf16(x1[2], x1[3]); *(u32x4*)(X + off) = xs_; }
;                 if (NEXT) { ss += ((x0.x * x0.x + x0.y * x0.y) + (x0.z * x0.z + x0.w * x0.w)) + ((x1.x * x1.x + x1.y * x1.y) + (x1.z * x1.z + x1.w * x1.w));
;                     const float* gp_ = gam + (size_t)sq * DM + col0 + bj * HALF; const f32x4 y0 = x0 * *(const f32x4*)gp_, y1 = x1 * *(const f32x4*)(gp_ + 4);
;                     u32x4 w; w.x = cvt_pk_bf16(y0[0], y0[1]); w.y = cvt_pk_bf16(y0[2], y0[3]); w.z = cvt_pk_bf16(y1[0], y1[1]); w.w = cvt_pk_bf16(y1[2], y1[3]);
;                     *(u32x4*)(XB + off) = w; } }
;             if (NEXT) { ss += __shfl_xor(ss, 16); ss += __shfl_xor(ss, 32); if (fq == 0) SSQ[(size_t)row * 16 + slot] = ss; } }
	v_lshlrev_b64 v[130:131], 6, v[184:185]
	v_lshl_add_u64 v[130:131], s[12:13], 0, v[130:131]
	v_lshl_add_u64 v[130:131], s[28:29], 2, v[130:131]
	s_waitcnt lgkmcnt(0)
	v_add_f32_e32 v128, v128, v129
	global_store_dword v[130:131], v128, off
.LBB0_559:
	s_or_b64 exec, exec, s[30:31]
	v_lshlrev_b32_e32 v128, 16, v150
	s_waitcnt lgkmcnt(0)
	v_and_b32_e32 v129, 0xffff0000, v150
	v_lshlrev_b32_e32 v130, 16, v151
	v_and_b32_e32 v131, 0xffff0000, v151
	v_lshlrev_b32_e32 v132, 16, v152
	v_and_b32_e32 v133, 0xffff0000, v152
	v_lshlrev_b32_e32 v150, 16, v153
	v_and_b32_e32 v151, 0xffff0000, v153
	v_pk_fma_f32 v[130:131], v[120:121], v[180:181], v[130:131]
	v_pk_fma_f32 v[128:129], v[118:119], v[178:179], v[128:129]
	v_pk_fma_f32 v[150:151], v[116:117], v[176:177], v[150:151]
	v_pk_fma_f32 v[132:133], v[114:115], v[174:175], v[132:133]
	v_cvt_pk_bf16_f32 v114, v128, v129
	v_cvt_pk_bf16_f32 v115, v130, v131
	v_lshlrev_b64 v[152:153], 10, v[194:195]
	v_cvt_pk_bf16_f32 v116, v132, v133
	v_cvt_pk_bf16_f32 v117, v150, v151
	global_store_dwordx4 v[196:197], v[114:117], off
	ds_read_b128 v[114:117], v255
	s_nop 0
	ds_read_b128 v[118:121], v255 offset:16
	v_lshl_add_u64 v[152:153], v[152:153], 0, v[170:171]
	v_lshlrev_b32_e32 v196, 16, v146
	v_and_b32_e32 v197, 0xffff0000, v146
	v_lshlrev_b32_e32 v146, 16, v147
	v_and_b32_e32 v147, 0xffff0000, v147
	v_lshlrev_b32_e32 v206, 16, v148
	v_and_b32_e32 v207, 0xffff0000, v148
	v_lshlrev_b32_e32 v148, 16, v149
	v_and_b32_e32 v149, 0xffff0000, v149
	v_lshlrev_b64 v[152:153], 1, v[152:153]
	v_pk_fma_f32 v[108:109], v[108:109], v[144:145], v[146:147]
	v_pk_fma_f32 v[146:147], v[106:107], v[142:143], v[196:197]
	v_pk_fma_f32 v[148:149], v[104:105], v[140:141], v[148:149]
	v_pk_fma_f32 v[196:197], v[102:103], v[138:139], v[206:207]
	v_lshl_add_u64 v[106:107], s[10:11], 0, v[152:153]
	v_or_b32_e32 v152, 0x100, v152
	v_lshl_add_u64 v[206:207], s[0:1], 0, v[152:153]
	s_waitcnt lgkmcnt(0)
	v_pk_mul_f32 v[104:105], v[130:131], v[116:117]
	v_pk_mul_f32 v[102:103], v[128:129], v[114:115]
	s_waitcnt lgkmcnt(0)
	v_pk_mul_f32 v[114:115], v[150:151], v[120:121]
	v_pk_mul_f32 v[116:117], v[132:133], v[118:119]
	v_cvt_pk_bf16_f32 v102, v102, v103
	v_cvt_pk_bf16_f32 v103, v104, v105
	v_mul_f32_e32 v118, v133, v133
	v_cvt_pk_bf16_f32 v104, v116, v117
	v_cvt_pk_bf16_f32 v105, v114, v115
	global_store_dwordx4 v[106:107], v[102:105], off
	v_mul_f32_e32 v119, v151, v151
	v_mul_f32_e32 v120, v147, v147
	v_cvt_pk_bf16_f32 v102, v146, v147
	v_cvt_pk_bf16_f32 v103, v108, v109
	v_cvt_pk_bf16_f32 v104, v196, v197
	v_cvt_pk_bf16_f32 v105, v148, v149
	global_store_dwordx4 v[206:207], v[102:105], off
	ds_read_b128 v[104:107], v255 offset:32
	s_nop 0
	ds_read_b128 v[114:117], v255 offset:48
	v_mul_f32_e32 v102, v129, v129
	v_mul_f32_e32 v103, v131, v131
	v_mul_f32_e32 v121, v109, v109
	v_mul_f32_e32 v129, v197, v197
	v_mul_f32_e32 v131, v149, v149
	v_fmac_f32_e32 v102, v128, v128
	v_fmac_f32_e32 v103, v130, v130
	v_fmac_f32_e32 v118, v132, v132
	v_fmac_f32_e32 v119, v150, v150
	v_fmac_f32_e32 v120, v146, v146
	v_fmac_f32_e32 v121, v108, v108
	v_fmac_f32_e32 v129, v196, v196
	v_fmac_f32_e32 v131, v148, v148
	v_add_f32_e32 v102, v102, v103
	v_add_f32_e32 v103, v118, v119
	v_add_f32_e32 v118, v120, v121
	v_add_f32_e32 v119, v129, v131
	v_add_f32_e32 v102, v102, v103
	v_add_f32_e32 v103, v118, v119
	v_add_f32_e32 v102, v102, v103
	ds_bpermute_b32 v103, v126, v102
	s_waitcnt lgkmcnt(0)
	v_add_f32_e32 v102, v102, v103
	ds_bpermute_b32 v103, v127, v102
	s_waitcnt lgkmcnt(0)
	v_pk_mul_f32 v[106:107], v[108:109], v[106:107]
	v_pk_mul_f32 v[104:105], v[146:147], v[104:105]
	s_waitcnt lgkmcnt(0)
	v_pk_mul_f32 v[108:109], v[148:149], v[116:117]
	v_pk_mul_f32 v[114:115], v[196:197], v[114:115]
	v_cvt_pk_bf16_f32 v104, v104, v105
	v_cvt_pk_bf16_f32 v105, v106, v107
	s_nop 0
	v_cvt_pk_bf16_f32 v106, v114, v115
	v_cvt_pk_bf16_f32 v107, v108, v109
	v_lshl_add_u64 v[108:109], s[10:11], 0, v[152:153]
	global_store_dwordx4 v[108:109], v[104:107], off
	s_and_saveexec_b64 s[30:31], s[4:5]
	s_cbranch_execz .LBB0_561
	v_lshlrev_b64 v[104:105], 6, v[194:195]
	v_lshl_add_u64 v[104:105], s[12:13], 0, v[104:105]
	v_lshl_add_u64 v[104:105], s[28:29], 2, v[104:105]
	s_waitcnt lgkmcnt(0)
	v_add_f32_e32 v102, v102, v103
	global_store_dword v[104:105], v102, off
; __device__ __forceinline__ void unpack8(const v4u w, float (&o)[8]) { o[0] = bflo(w.x); o[1] = bfhi(w.x); o[2] = bflo(w.y); o[3] = bfhi(w.y); o[4] = bflo(w.z); o[5] = bfhi(w.z); o[6] = bflo(w.w); o[7] = bfhi(w.w); }
; __device__ __forceinline__ unsigned cvt_pk_bf16(float lo, float hi) { unsigned r; asm volatile("v_cvt_pk_bf16_f32 %0, %1, %2" : "=v"(r) : "v"(lo), "v"(hi)); return r; }
;     template <int AI> __device__ __forceinline__ void half_rows(AccT acc, int row0, int col0, int slot, int sq, int fq, const f32x4 (&gsc)[4]) const {
;     ...
;         for (int m = 0; m < 4; ++m) { const int row = row0 + m * 16;
;             float ss = 0.f;
; #pragma unroll
;             for (int bj = 0; bj < 2; ++bj) { const size_t off = (size_t)row * DM + col0 + bj * HALF;
;                 float xi[8]; unpack8(xw[m][bj], xi);
;                 const f32x4 x0 = (f32x4){xi[0], xi[1], xi[2], xi[3]} + gsc[bj * 2] * acc[AI][bj][m][0], x1 = (f32x4){xi[4], xi[5], xi[6], xi[7]} + gsc[bj * 2 + 1] * acc[AI][bj][m][1];
;                 { u32x4 xs_; xs_.x = cvt_pk_bf16(x0[0], x0[1]); xs_.y = cvt_pk_bf16(x0[2], x0[3]); xs_.z = cvt_pk_bf16(x1[0], x1[1]); xs_.w = cvt_pk_bf16(x1[2], x1[3]); *(u32x4*)(X + off) = xs_; }
;                 if (NEXT) { ss += ((x0.x * x0.x + x0.y * x0.y) + (x0.z * x0.z + x0.w * x0.w)) + ((x1.x * x1.x + x1.y * x1.y) + (x1.z * x1.z + x1.w * x1.w));
;                     const float* gp_ = gam + (size_t)sq * DM + col0 + bj * HALF; const f32x4 y0 = x0 * *(const f32x4*)gp_, y1 = x1 * *(const f32x4*)(gp_ + 4);
;                     u32x4 w; w.x = cvt_pk_bf16(y0[0], y0[1]); w.y = cvt_pk_bf16(y0[2], y0[3]); w.z = cvt_pk_bf16(y1[0], y1[1]); w.w = cvt_pk_bf16(y1[2], y1[3]);
;                     *(u32x4*)(XB + off) = w; } }
;             if (NEXT) { ss += __shfl_xor(ss, 16); ss += __shfl_xor(ss, 32); if (fq == 0) SSQ[(size_t)row * 16 + slot] = ss; } }
.LBB0_561:
	s_or_b64 exec, exec, s[30:31]
	v_lshlrev_b32_e32 v102, 16, v134
	s_waitcnt lgkmcnt(0)
	v_and_b32_e32 v103, 0xffff0000, v134
	v_lshlrev_b32_e32 v104, 16, v135
	v_and_b32_e32 v105, 0xffff0000, v135
	v_lshlrev_b32_e32 v106, 16, v136
	v_and_b32_e32 v107, 0xffff0000, v136
	v_lshlrev_b32_e32 v108, 16, v137
	v_and_b32_e32 v109, 0xffff0000, v137
	v_pk_fma_f32 v[104:105], v[96:97], v[180:181], v[104:105]
	v_pk_fma_f32 v[102:103], v[94:95], v[178:179], v[102:103]
	v_pk_fma_f32 v[108:109], v[92:93], v[176:177], v[108:109]
	v_pk_fma_f32 v[106:107], v[90:91], v[174:175], v[106:107]
	v_cvt_pk_bf16_f32 v90, v102, v103
	v_cvt_pk_bf16_f32 v91, v104, v105
	v_lshlrev_b64 v[114:115], 10, v[190:191]
	v_cvt_pk_bf16_f32 v92, v106, v107
	v_cvt_pk_bf16_f32 v93, v108, v109
	global_store_dwordx4 v[192:193], v[90:93], off
	ds_read_b128 v[90:93], v255
	s_nop 0
	ds_read_b128 v[94:97], v255 offset:16
	v_lshl_add_u64 v[114:115], v[114:115], 0, v[170:171]
	v_lshlrev_b32_e32 v116, 16, v122
	v_and_b32_e32 v117, 0xffff0000, v122
	v_lshlrev_b32_e32 v118, 16, v123
	v_and_b32_e32 v119, 0xffff0000, v123
	v_lshlrev_b32_e32 v120, 16, v124
	v_and_b32_e32 v121, 0xffff0000, v124
	v_lshlrev_b32_e32 v122, 16, v125
	v_and_b32_e32 v123, 0xffff0000, v125
	v_lshlrev_b64 v[114:115], 1, v[114:115]
	v_pk_fma_f32 v[116:117], v[86:87], v[142:143], v[116:117]
	v_pk_fma_f32 v[122:123], v[84:85], v[140:141], v[122:123]
	v_pk_fma_f32 v[120:121], v[82:83], v[138:139], v[120:121]
	v_lshl_add_u64 v[86:87], s[10:11], 0, v[114:115]
	v_or_b32_e32 v114, 0x100, v114
	v_pk_fma_f32 v[118:119], v[88:89], v[144:145], v[118:119]
	v_lshl_add_u64 v[88:89], s[0:1], 0, v[114:115]
	s_waitcnt lgkmcnt(0)
	v_pk_mul_f32 v[84:85], v[104:105], v[92:93]
	v_pk_mul_f32 v[82:83], v[102:103], v[90:91]
	s_waitcnt lgkmcnt(0)
	v_pk_mul_f32 v[90:91], v[108:109], v[96:97]
	v_pk_mul_f32 v[92:93], v[106:107], v[94:95]
	v_cvt_pk_bf16_f32 v82, v82, v83
	v_cvt_pk_bf16_f32 v83, v84, v85
	v_mul_f32_e32 v94, v117, v117
	v_cvt_pk_bf16_f32 v84, v92, v93
	v_cvt_pk_bf16_f32 v85, v90, v91
	global_store_dwordx4 v[86:87], v[82:85], off
	v_mul_f32_e32 v92, v107, v107
	v_mul_f32_e32 v93, v109, v109
	v_cvt_pk_bf16_f32 v82, v116, v117
	v_cvt_pk_bf16_f32 v83, v118, v119
	v_cvt_pk_bf16_f32 v84, v120, v121
	v_cvt_pk_bf16_f32 v85, v122, v123
	global_store_dwordx4 v[88:89], v[82:85], off
	ds_read_b128 v[84:87], v255 offset:32
	s_nop 0
	ds_read_b128 v[88:91], v255 offset:48
	v_mul_f32_e32 v82, v103, v103
	v_mul_f32_e32 v83, v105, v105
	v_mul_f32_e32 v95, v119, v119
	v_mul_f32_e32 v96, v121, v121
	v_mul_f32_e32 v97, v123, v123
	v_fmac_f32_e32 v82, v102, v102
	v_fmac_f32_e32 v83, v104, v104
	v_fmac_f32_e32 v92, v106, v106
	v_fmac_f32_e32 v93, v108, v108
	v_fmac_f32_e32 v94, v116, v116
	v_fmac_f32_e32 v95, v118, v118
	v_fmac_f32_e32 v96, v120, v120
	v_fmac_f32_e32 v97, v122, v122
	v_add_f32_e32 v82, v82, v83
	v_add_f32_e32 v83, v92, v93
	v_add_f32_e32 v92, v94, v95
	v_add_f32_e32 v93, v96, v97
	v_add_f32_e32 v82, v82, v83
	v_add_f32_e32 v83, v92, v93
	v_add_f32_e32 v82, v82, v83
	ds_bpermute_b32 v83, v126, v82
	s_waitcnt lgkmcnt(0)
	v_add_f32_e32 v82, v82, v83
	ds_bpermute_b32 v83, v127, v82
	s_waitcnt lgkmcnt(0)
	v_pk_mul_f32 v[86:87], v[118:119], v[86:87]
	v_pk_mul_f32 v[84:85], v[116:117], v[84:85]
	s_waitcnt lgkmcnt(0)
	v_pk_mul_f32 v[88:89], v[120:121], v[88:89]
	v_cvt_pk_bf16_f32 v84, v84, v85
	v_cvt_pk_bf16_f32 v85, v86, v87
	v_pk_mul_f32 v[90:91], v[122:123], v[90:91]
	v_cvt_pk_bf16_f32 v86, v88, v89
	v_lshl_add_u64 v[88:89], s[10:11], 0, v[114:115]
	v_cvt_pk_bf16_f32 v87, v90, v91
	global_store_dwordx4 v[88:89], v[84:87], off
	s_and_saveexec_b64 s[30:31], s[4:5]
	s_cbranch_execz .LBB0_563
	v_lshlrev_b64 v[84:85], 6, v[190:191]
	v_lshl_add_u64 v[84:85], s[12:13], 0, v[84:85]
	v_lshl_add_u64 v[84:85], s[28:29], 2, v[84:85]
	s_waitcnt lgkmcnt(0)
	v_add_f32_e32 v82, v82, v83
	global_store_dword v[84:85], v82, off
.LBB0_563:
	s_or_b64 exec, exec, s[30:31]
	v_lshlrev_b32_e32 v82, 16, v110
	s_waitcnt lgkmcnt(0)
	v_and_b32_e32 v83, 0xffff0000, v110
	v_lshlrev_b32_e32 v84, 16, v111
	v_and_b32_e32 v85, 0xffff0000, v111
	v_lshlrev_b32_e32 v86, 16, v112
	v_and_b32_e32 v87, 0xffff0000, v112
	v_lshlrev_b32_e32 v88, 16, v113
	v_and_b32_e32 v89, 0xffff0000, v113
	v_pk_fma_f32 v[84:85], v[80:81], v[180:181], v[84:85]
	v_pk_fma_f32 v[82:83], v[78:79], v[178:179], v[82:83]
	v_pk_fma_f32 v[88:89], v[76:77], v[176:177], v[88:89]
	v_pk_fma_f32 v[86:87], v[74:75], v[174:175], v[86:87]
	v_cvt_pk_bf16_f32 v74, v82, v83
	v_cvt_pk_bf16_f32 v75, v84, v85
	v_lshlrev_b64 v[90:91], 10, v[186:187]
	v_cvt_pk_bf16_f32 v76, v86, v87
	v_cvt_pk_bf16_f32 v77, v88, v89
	global_store_dwordx4 v[188:189], v[74:77], off
	ds_read_b128 v[74:77], v255
	s_nop 0
	ds_read_b128 v[78:81], v255 offset:16
	v_lshl_add_u64 v[90:91], v[90:91], 0, v[170:171]
	v_lshlrev_b32_e32 v92, 16, v98
	v_and_b32_e32 v93, 0xffff0000, v98
	v_lshlrev_b32_e32 v94, 16, v99
	v_and_b32_e32 v95, 0xffff0000, v99
	v_lshlrev_b32_e32 v96, 16, v100
	v_and_b32_e32 v97, 0xffff0000, v100
	v_lshlrev_b32_e32 v98, 16, v101
	v_and_b32_e32 v99, 0xffff0000, v101
	v_lshlrev_b64 v[90:91], 1, v[90:91]
	v_pk_fma_f32 v[92:93], v[70:71], v[142:143], v[92:93]
	v_pk_fma_f32 v[98:99], v[68:69], v[140:141], v[98:99]
	v_pk_fma_f32 v[96:97], v[66:67], v[138:139], v[96:97]
	v_lshl_add_u64 v[70:71], s[10:11], 0, v[90:91]
	v_or_b32_e32 v90, 0x100, v90
	v_pk_fma_f32 v[94:95], v[72:73], v[144:145], v[94:95]
	v_lshl_add_u64 v[72:73], s[0:1], 0, v[90:91]
	s_waitcnt lgkmcnt(0)
	v_pk_mul_f32 v[68:69], v[84:85], v[76:77]
	v_pk_mul_f32 v[66:67], v[82:83], v[74:75]
	s_waitcnt lgkmcnt(0)
; __device__ __forceinline__ void unpack8(const v4u w, float (&o)[8]) { o[0] = bflo(w.x); o[1] = bfhi(w.x); o[2] = bflo(w.y); o[3] = bfhi(w.y); o[4] = bflo(w.z); o[5] = bfhi(w.z); o[6] = bflo(w.w); o[7] = bfhi(w.w); }
; __device__ __forceinline__ unsigned cvt_pk_bf16(float lo, float hi) { unsigned r; asm volatile("v_cvt_pk_bf16_f32 %0, %1, %2" : "=v"(r) : "v"(lo), "v"(hi)); return r; }
;     template <int AI> __device__ __forceinline__ void half_rows(AccT acc, int row0, int col0, int slot, int sq, int fq, const f32x4 (&gsc)[4]) const {
;     ...
;             for (int bj = 0; bj < 2; ++bj) xw[m][bj] = *(const v4u*)(X + (size_t)(row0 + m * 16) * DM + col0 + bj * HALF);
; #pragma unroll
;         for (int m = 0; m < 4; ++m) { const int row = row0 + m * 16;
;             float ss = 0.f;
; #pragma unroll
;             for (int bj = 0; bj < 2; ++bj) { const size_t off = (size_t)row * DM + col0 + bj * HALF;
;                 float xi[8]; unpack8(xw[m][bj], xi);
;                 const f32x4 x0 = (f32x4){xi[0], xi[1], xi[2], xi[3]} + gsc[bj * 2] * acc[AI][bj][m][0], x1 = (f32x4){xi[4], xi[5], xi[6], xi[7]} + gsc[bj * 2 + 1] * acc[AI][bj][m][1];
;                 { u32x4 xs_; xs_.x = cvt_pk_bf16(x0[0], x0[1]); xs_.y = cvt_pk_bf16(x0[2], x0[3]); xs_.z = cvt_pk_bf16(x1[0], x1[1]); xs_.w = cvt_pk_bf16(x1[2], x1[3]); *(u32x4*)(X + off) = xs_; }
;                 if (NEXT) { ss += ((x0.x * x0.x + x0.y * x0.y) + (x0.z * x0.z + x0.w * x0.w)) + ((x1.x * x1.x + x1.y * x1.y) + (x1.z * x1.z + x1.w * x1.w));
;                     const float* gp_ = gam + (size_t)sq * DM + col0 + bj * HALF; const f32x4 y0 = x0 * *(const f32x4*)gp_, y1 = x1 * *(const f32x4*)(gp_ + 4);
;                     u32x4 w; w.x = cvt_pk_bf16(y0[0], y0[1]); w.y = cvt_pk_bf16(y0[2], y0[3]); w.z = cvt_pk_bf16(y1[0], y1[1]); w.w = cvt_pk_bf16(y1[2], y1[3]);
;                     *(u32x4*)(XB + off) = w; } }
;             if (NEXT) { ss += __shfl_xor(ss, 16); ss += __shfl_xor(ss, 32); if (fq == 0) SSQ[(size_t)row * 16 + slot] = ss; } }
	v_pk_mul_f32 v[74:75], v[88:89], v[80:81]
	v_pk_mul_f32 v[76:77], v[86:87], v[78:79]
	v_cvt_pk_bf16_f32 v66, v66, v67
	v_cvt_pk_bf16_f32 v67, v68, v69
	v_mul_f32_e32 v78, v93, v93
	v_cvt_pk_bf16_f32 v68, v76, v77
	v_cvt_pk_bf16_f32 v69, v74, v75
	global_store_dwordx4 v[70:71], v[66:69], off
	v_mul_f32_e32 v76, v87, v87
	v_mul_f32_e32 v77, v89, v89
	v_cvt_pk_bf16_f32 v66, v92, v93
	v_cvt_pk_bf16_f32 v67, v94, v95
	v_cvt_pk_bf16_f32 v68, v96, v97
	v_cvt_pk_bf16_f32 v69, v98, v99
	global_store_dwordx4 v[72:73], v[66:69], off
	ds_read_b128 v[68:71], v255 offset:32
	s_nop 0
	ds_read_b128 v[72:75], v255 offset:48
	v_mul_f32_e32 v66, v83, v83
	v_mul_f32_e32 v67, v85, v85
	v_mul_f32_e32 v79, v95, v95
	v_mul_f32_e32 v80, v97, v97
	v_mul_f32_e32 v81, v99, v99
	v_fmac_f32_e32 v66, v82, v82
	v_fmac_f32_e32 v67, v84, v84
	v_fmac_f32_e32 v76, v86, v86
	v_fmac_f32_e32 v77, v88, v88
	v_fmac_f32_e32 v78, v92, v92
	v_fmac_f32_e32 v79, v94, v94
	v_fmac_f32_e32 v80, v96, v96
	v_fmac_f32_e32 v81, v98, v98
	v_add_f32_e32 v66, v66, v67
	v_add_f32_e32 v67, v76, v77
	v_add_f32_e32 v76, v78, v79
	v_add_f32_e32 v77, v80, v81
	v_add_f32_e32 v66, v66, v67
	v_add_f32_e32 v67, v76, v77
	v_add_f32_e32 v66, v66, v67
	ds_bpermute_b32 v67, v126, v66
	s_waitcnt lgkmcnt(0)
	v_add_f32_e32 v66, v66, v67
	ds_bpermute_b32 v67, v127, v66
	s_waitcnt lgkmcnt(0)
	v_pk_mul_f32 v[70:71], v[94:95], v[70:71]
	v_pk_mul_f32 v[68:69], v[92:93], v[68:69]
	s_waitcnt lgkmcnt(0)
	v_pk_mul_f32 v[72:73], v[96:97], v[72:73]
	v_cvt_pk_bf16_f32 v68, v68, v69
	v_cvt_pk_bf16_f32 v69, v70, v71
	v_pk_mul_f32 v[74:75], v[98:99], v[74:75]
	v_cvt_pk_bf16_f32 v70, v72, v73
	v_lshl_add_u64 v[72:73], s[10:11], 0, v[90:91]
	v_cvt_pk_bf16_f32 v71, v74, v75
	global_store_dwordx4 v[72:73], v[68:71], off
	s_and_saveexec_b64 s[30:31], s[4:5]
	s_cbranch_execz .LBB0_565
	v_lshlrev_b64 v[68:69], 6, v[186:187]
	v_lshl_add_u64 v[68:69], s[12:13], 0, v[68:69]
	v_lshl_add_u64 v[68:69], s[28:29], 2, v[68:69]
	s_waitcnt lgkmcnt(0)
	v_add_f32_e32 v66, v66, v67
	global_store_dword v[68:69], v66, off
.LBB0_565:
	s_or_b64 exec, exec, s[30:31]
	v_add_u32_e32 v102, 0x80, v184
	v_ashrrev_i32_e32 v103, 31, v102
	s_waitcnt lgkmcnt(0)
	v_lshlrev_b64 v[66:67], 11, v[102:103]
	v_lshl_add_u64 v[112:113], v[182:183], 0, v[66:67]
	global_load_dwordx4 v[104:107], v[112:113], off
	v_add_u32_e32 v98, 0x90, v184
	v_add_u32_e32 v94, 0xa0, v184
	v_add_u32_e32 v90, 0xb0, v184
	v_ashrrev_i32_e32 v99, 31, v98
	v_ashrrev_i32_e32 v95, 31, v94
	v_ashrrev_i32_e32 v91, 31, v90
	v_lshlrev_b64 v[66:67], 11, v[98:99]
	v_lshlrev_b64 v[68:69], 11, v[94:95]
	v_lshlrev_b64 v[70:71], 11, v[90:91]
	v_lshl_add_u64 v[100:101], v[182:183], 0, v[66:67]
	v_lshl_add_u64 v[96:97], v[182:183], 0, v[68:69]
	v_lshl_add_u64 v[92:93], v[182:183], 0, v[70:71]
	global_load_dwordx4 v[108:111], v[112:113], off offset:256
	global_load_dwordx4 v[86:89], v[100:101], off
	global_load_dwordx4 v[82:85], v[100:101], off offset:256
	global_load_dwordx4 v[78:81], v[96:97], off
	global_load_dwordx4 v[74:77], v[96:97], off offset:256
	global_load_dwordx4 v[70:73], v[92:93], off
	global_load_dwordx4 v[66:69], v[92:93], off offset:256
	s_waitcnt vmcnt(0) lgkmcnt(0)
	v_lshlrev_b32_e32 v114, 16, v104
	v_and_b32_e32 v115, 0xffff0000, v104
	v_lshlrev_b32_e32 v104, 16, v105
	v_and_b32_e32 v105, 0xffff0000, v105
	v_lshlrev_b32_e32 v116, 16, v106
	v_and_b32_e32 v117, 0xffff0000, v106
	v_lshlrev_b32_e32 v106, 16, v107
	v_and_b32_e32 v107, 0xffff0000, v107
	v_pk_fma_f32 v[104:105], v[64:65], v[180:181], v[104:105]
	v_pk_fma_f32 v[114:115], v[62:63], v[178:179], v[114:115]
	v_pk_fma_f32 v[106:107], v[60:61], v[176:177], v[106:107]
	v_pk_fma_f32 v[116:117], v[58:59], v[174:175], v[116:117]
	v_cvt_pk_bf16_f32 v58, v114, v115
	v_cvt_pk_bf16_f32 v59, v104, v105
	s_waitcnt lgkmcnt(0)
	v_lshlrev_b32_e32 v124, 16, v110
	v_cvt_pk_bf16_f32 v60, v116, v117
	v_cvt_pk_bf16_f32 v61, v106, v107
	global_store_dwordx4 v[112:113], v[58:61], off
	ds_read_b128 v[58:61], v255
	s_nop 0
	ds_read_b128 v[62:65], v255 offset:16
	v_lshlrev_b64 v[112:113], 10, v[102:103]
	v_lshl_add_u64 v[112:113], v[112:113], 0, v[170:171]
	v_lshlrev_b64 v[112:113], 1, v[112:113]
	v_and_b32_e32 v125, 0xffff0000, v110
	v_lshlrev_b32_e32 v110, 16, v111
	v_and_b32_e32 v111, 0xffff0000, v111
	v_lshl_add_u64 v[118:119], s[10:11], 0, v[112:113]
	v_or_b32_e32 v112, 0x100, v112
	v_lshlrev_b32_e32 v122, 16, v108
	v_and_b32_e32 v123, 0xffff0000, v108
	v_lshlrev_b32_e32 v108, 16, v109
	v_and_b32_e32 v109, 0xffff0000, v109
	v_pk_fma_f32 v[110:111], v[52:53], v[140:141], v[110:111]
	v_pk_fma_f32 v[124:125], v[50:51], v[138:139], v[124:125]
	v_lshl_add_u64 v[120:121], s[0:1], 0, v[112:113]
	v_pk_fma_f32 v[108:109], v[56:57], v[144:145], v[108:109]
	v_pk_fma_f32 v[122:123], v[54:55], v[142:143], v[122:123]
	s_waitcnt lgkmcnt(0)
	v_pk_mul_f32 v[52:53], v[104:105], v[60:61]
	v_pk_mul_f32 v[50:51], v[114:115], v[58:59]
	s_waitcnt lgkmcnt(0)
	v_pk_mul_f32 v[54:55], v[106:107], v[64:65]
	v_pk_mul_f32 v[56:57], v[116:117], v[62:63]
	v_cvt_pk_bf16_f32 v50, v50, v51
	v_cvt_pk_bf16_f32 v51, v52, v53
	v_mul_f32_e32 v60, v117, v117
	v_cvt_pk_bf16_f32 v52, v56, v57
	v_cvt_pk_bf16_f32 v53, v54, v55
	global_store_dwordx4 v[118:119], v[50:53], off
	v_mul_f32_e32 v61, v107, v107
	v_mul_f32_e32 v62, v123, v123
	v_cvt_pk_bf16_f32 v50, v122, v123
	v_cvt_pk_bf16_f32 v51, v108, v109
	v_cvt_pk_bf16_f32 v52, v124, v125
	v_cvt_pk_bf16_f32 v53, v110, v111
	global_store_dwordx4 v[120:121], v[50:53], off
	ds_read_b128 v[52:55], v255 offset:32
	s_nop 0
	ds_read_b128 v[56:59], v255 offset:48
	v_mul_f32_e32 v50, v115, v115
	v_mul_f32_e32 v51, v105, v105
	v_mul_f32_e32 v63, v109, v109
	v_mul_f32_e32 v64, v125, v125
	v_mul_f32_e32 v65, v111, v111
	v_fmac_f32_e32 v50, v114, v114
	v_fmac_f32_e32 v51, v104, v104
	v_fmac_f32_e32 v60, v116, v116
	v_fmac_f32_e32 v61, v106, v106
	v_fmac_f32_e32 v62, v122, v122
	v_fmac_f32_e32 v63, v108, v108
	v_fmac_f32_e32 v64, v124, v124
	v_fmac_f32_e32 v65, v110, v110
	v_add_f32_e32 v50, v50, v51
	v_add_f32_e32 v51, v60, v61
	v_add_f32_e32 v60, v62, v63
	v_add_f32_e32 v61, v64, v65
	v_add_f32_e32 v50, v50, v51
	v_add_f32_e32 v51, v60, v61
	v_add_f32_e32 v50, v50, v51
	ds_bpermute_b32 v51, v126, v50
	s_waitcnt lgkmcnt(0)
	v_add_f32_e32 v50, v50, v51
	ds_bpermute_b32 v51, v127, v50
	s_waitcnt lgkmcnt(0)
	v_pk_mul_f32 v[54:55], v[108:109], v[54:55]
	v_pk_mul_f32 v[52:53], v[122:123], v[52:53]
	s_waitcnt lgkmcnt(0)
	v_pk_mul_f32 v[56:57], v[124:125], v[56:57]
	v_cvt_pk_bf16_f32 v52, v52, v53
	v_cvt_pk_bf16_f32 v53, v54, v55
	v_pk_mul_f32 v[58:59], v[110:111], v[58:59]
	v_cvt_pk_bf16_f32 v54, v56, v57
	v_lshl_add_u64 v[56:57], s[10:11], 0, v[112:113]
	v_cvt_pk_bf16_f32 v55, v58, v59
	global_store_dwordx4 v[56:57], v[52:55], off
	s_and_saveexec_b64 s[30:31], s[4:5]
	s_cbranch_execz .LBB0_567
	v_lshlrev_b64 v[52:53], 6, v[102:103]
	v_lshl_add_u64 v[52:53], s[12:13], 0, v[52:53]
	v_lshl_add_u64 v[52:53], s[28:29], 2, v[52:53]
	s_waitcnt lgkmcnt(0)
	v_add_f32_e32 v50, v50, v51
	global_store_dword v[52:53], v50, off
; __device__ __forceinline__ void unpack8(const v4u w, float (&o)[8]) { o[0] = bflo(w.x); o[1] = bfhi(w.x); o[2] = bflo(w.y); o[3] = bfhi(w.y); o[4] = bflo(w.z); o[5] = bfhi(w.z); o[6] = bflo(w.w); o[7] = bfhi(w.w); }
; __device__ __forceinline__ unsigned cvt_pk_bf16(float lo, float hi) { unsigned r; asm volatile("v_cvt_pk_bf16_f32 %0, %1, %2" : "=v"(r) : "v"(lo), "v"(hi)); return r; }
;     template <int AI> __device__ __forceinline__ void half_rows(AccT acc, int row0, int col0, int slot, int sq, int fq, const f32x4 (&gsc)[4]) const {
;     ...
;         for (int m = 0; m < 4; ++m) { const int row = row0 + m * 16;
;             float ss = 0.f;
; #pragma unroll
;             for (int bj = 0; bj < 2; ++bj) { const size_t off = (size_t)row * DM + col0 + bj * HALF;
;                 float xi[8]; unpack8(xw[m][bj], xi);
;                 const f32x4 x0 = (f32x4){xi[0], xi[1], xi[2], xi[3]} + gsc[bj * 2] * acc[AI][bj][m][0], x1 = (f32x4){xi[4], xi[5], xi[6], xi[7]} + gsc[bj * 2 + 1] * acc[AI][bj][m][1];
;                 { u32x4 xs_; xs_.x = cvt_pk_bf16(x0[0], x0[1]); xs_.y = cvt_pk_bf16(x0[2], x0[3]); xs_.z = cvt_pk_bf16(x1[0], x1[1]); xs_.w = cvt_pk_bf16(x1[2], x1[3]); *(u32x4*)(X + off) = xs_; }
;                 if (NEXT) { ss += ((x0.x * x0.x + x0.y * x0.y) + (x0.z * x0.z + x0.w * x0.w)) + ((x1.x * x1.x + x1.y * x1.y) + (x1.z * x1.z + x1.w * x1.w));
;                     const float* gp_ = gam + (size_t)sq * DM + col0 + bj * HALF; const f32x4 y0 = x0 * *(const f32x4*)gp_, y1 = x1 * *(const f32x4*)(gp_ + 4);
;                     u32x4 w; w.x = cvt_pk_bf16(y0[0], y0[1]); w.y = cvt_pk_bf16(y0[2], y0[3]); w.z = cvt_pk_bf16(y1[0], y1[1]); w.w = cvt_pk_bf16(y1[2], y1[3]);
;                     *(u32x4*)(XB + off) = w; } }
;             if (NEXT) { ss += __shfl_xor(ss, 16); ss += __shfl_xor(ss, 32); if (fq == 0) SSQ[(size_t)row * 16 + slot] = ss; } }
.LBB0_567:
	s_or_b64 exec, exec, s[30:31]
	v_lshlrev_b32_e32 v50, 16, v86
	s_waitcnt lgkmcnt(0)
	v_and_b32_e32 v51, 0xffff0000, v86
	v_lshlrev_b32_e32 v52, 16, v87
	v_and_b32_e32 v53, 0xffff0000, v87
	v_lshlrev_b32_e32 v54, 16, v88
	v_and_b32_e32 v55, 0xffff0000, v88
	v_lshlrev_b32_e32 v56, 16, v89
	v_and_b32_e32 v57, 0xffff0000, v89
	v_pk_fma_f32 v[52:53], v[48:49], v[180:181], v[52:53]
	v_pk_fma_f32 v[50:51], v[46:47], v[178:179], v[50:51]
	v_pk_fma_f32 v[56:57], v[44:45], v[176:177], v[56:57]
	v_pk_fma_f32 v[54:55], v[42:43], v[174:175], v[54:55]
	v_cvt_pk_bf16_f32 v42, v50, v51
	v_cvt_pk_bf16_f32 v43, v52, v53
	v_lshlrev_b64 v[58:59], 10, v[98:99]
	v_cvt_pk_bf16_f32 v44, v54, v55
	v_cvt_pk_bf16_f32 v45, v56, v57
	global_store_dwordx4 v[100:101], v[42:45], off
	ds_read_b128 v[42:45], v255
	s_nop 0
	ds_read_b128 v[46:49], v255 offset:16
	v_lshl_add_u64 v[58:59], v[58:59], 0, v[170:171]
	v_lshlrev_b32_e32 v60, 16, v82
	v_and_b32_e32 v61, 0xffff0000, v82
	v_lshlrev_b32_e32 v62, 16, v83
	v_and_b32_e32 v63, 0xffff0000, v83
	v_lshlrev_b32_e32 v64, 16, v84
	v_and_b32_e32 v65, 0xffff0000, v84
	v_lshlrev_b32_e32 v82, 16, v85
	v_and_b32_e32 v83, 0xffff0000, v85
	v_lshlrev_b64 v[58:59], 1, v[58:59]
	v_pk_fma_f32 v[60:61], v[38:39], v[142:143], v[60:61]
	v_pk_fma_f32 v[82:83], v[36:37], v[140:141], v[82:83]
	v_pk_fma_f32 v[64:65], v[34:35], v[138:139], v[64:65]
	v_lshl_add_u64 v[38:39], s[10:11], 0, v[58:59]
	v_or_b32_e32 v58, 0x100, v58
	v_pk_fma_f32 v[62:63], v[40:41], v[144:145], v[62:63]
	v_lshl_add_u64 v[40:41], s[0:1], 0, v[58:59]
	s_waitcnt lgkmcnt(0)
	v_pk_mul_f32 v[36:37], v[52:53], v[44:45]
	v_pk_mul_f32 v[34:35], v[50:51], v[42:43]
	s_waitcnt lgkmcnt(0)
	v_pk_mul_f32 v[42:43], v[56:57], v[48:49]
	v_pk_mul_f32 v[44:45], v[54:55], v[46:47]
	v_cvt_pk_bf16_f32 v34, v34, v35
	v_cvt_pk_bf16_f32 v35, v36, v37
	v_mul_f32_e32 v46, v61, v61
	v_cvt_pk_bf16_f32 v36, v44, v45
	v_cvt_pk_bf16_f32 v37, v42, v43
	global_store_dwordx4 v[38:39], v[34:37], off
	v_mul_f32_e32 v44, v55, v55
	v_mul_f32_e32 v45, v57, v57
	v_cvt_pk_bf16_f32 v34, v60, v61
	v_cvt_pk_bf16_f32 v35, v62, v63
	v_cvt_pk_bf16_f32 v36, v64, v65
	v_cvt_pk_bf16_f32 v37, v82, v83
	global_store_dwordx4 v[40:41], v[34:37], off
	ds_read_b128 v[36:39], v255 offset:32
	s_nop 0
	ds_read_b128 v[40:43], v255 offset:48
	v_mul_f32_e32 v34, v51, v51
	v_mul_f32_e32 v35, v53, v53
	v_mul_f32_e32 v47, v63, v63
	v_mul_f32_e32 v48, v65, v65
	v_mul_f32_e32 v49, v83, v83
	v_fmac_f32_e32 v34, v50, v50
	v_fmac_f32_e32 v35, v52, v52
	v_fmac_f32_e32 v44, v54, v54
	v_fmac_f32_e32 v45, v56, v56
	v_fmac_f32_e32 v46, v60, v60
	v_fmac_f32_e32 v47, v62, v62
	v_fmac_f32_e32 v48, v64, v64
	v_fmac_f32_e32 v49, v82, v82
	v_add_f32_e32 v34, v34, v35
	v_add_f32_e32 v35, v44, v45
	v_add_f32_e32 v44, v46, v47
	v_add_f32_e32 v45, v48, v49
	v_add_f32_e32 v34, v34, v35
	v_add_f32_e32 v35, v44, v45
	v_add_f32_e32 v34, v34, v35
	ds_bpermute_b32 v35, v126, v34
	s_waitcnt lgkmcnt(0)
	v_add_f32_e32 v34, v34, v35
	ds_bpermute_b32 v35, v127, v34
	s_waitcnt lgkmcnt(0)
	v_pk_mul_f32 v[38:39], v[62:63], v[38:39]
	v_pk_mul_f32 v[36:37], v[60:61], v[36:37]
	s_waitcnt lgkmcnt(0)
	v_pk_mul_f32 v[40:41], v[64:65], v[40:41]
	v_cvt_pk_bf16_f32 v36, v36, v37
	v_cvt_pk_bf16_f32 v37, v38, v39
	v_pk_mul_f32 v[42:43], v[82:83], v[42:43]
	v_cvt_pk_bf16_f32 v38, v40, v41
	v_lshl_add_u64 v[40:41], s[10:11], 0, v[58:59]
	v_cvt_pk_bf16_f32 v39, v42, v43
	global_store_dwordx4 v[40:41], v[36:39], off
	s_and_saveexec_b64 s[30:31], s[4:5]
	s_cbranch_execz .LBB0_569
	v_lshlrev_b64 v[36:37], 6, v[98:99]
	v_lshl_add_u64 v[36:37], s[12:13], 0, v[36:37]
	v_lshl_add_u64 v[36:37], s[28:29], 2, v[36:37]
	s_waitcnt lgkmcnt(0)
	v_add_f32_e32 v34, v34, v35
	global_store_dword v[36:37], v34, off
.LBB0_569:
	s_or_b64 exec, exec, s[30:31]
	v_lshlrev_b32_e32 v34, 16, v78
	s_waitcnt lgkmcnt(0)
	v_and_b32_e32 v35, 0xffff0000, v78
	v_lshlrev_b32_e32 v36, 16, v79
	v_and_b32_e32 v37, 0xffff0000, v79
	v_lshlrev_b32_e32 v38, 16, v80
	v_and_b32_e32 v39, 0xffff0000, v80
	v_lshlrev_b32_e32 v40, 16, v81
	v_and_b32_e32 v41, 0xffff0000, v81
	v_pk_fma_f32 v[36:37], v[32:33], v[180:181], v[36:37]
	v_pk_fma_f32 v[34:35], v[30:31], v[178:179], v[34:35]
	v_pk_fma_f32 v[40:41], v[28:29], v[176:177], v[40:41]
	v_pk_fma_f32 v[38:39], v[26:27], v[174:175], v[38:39]
	v_cvt_pk_bf16_f32 v26, v34, v35
	v_cvt_pk_bf16_f32 v27, v36, v37
	v_lshlrev_b64 v[42:43], 10, v[94:95]
	v_cvt_pk_bf16_f32 v28, v38, v39
	v_cvt_pk_bf16_f32 v29, v40, v41
	global_store_dwordx4 v[96:97], v[26:29], off
	ds_read_b128 v[26:29], v255
	s_nop 0
	ds_read_b128 v[30:33], v255 offset:16
	v_lshl_add_u64 v[42:43], v[42:43], 0, v[170:171]
	v_lshlrev_b32_e32 v44, 16, v74
	v_and_b32_e32 v45, 0xffff0000, v74
	v_lshlrev_b32_e32 v48, 16, v76
	v_and_b32_e32 v49, 0xffff0000, v76
	v_lshlrev_b32_e32 v50, 16, v77
	v_and_b32_e32 v51, 0xffff0000, v77
	v_lshlrev_b64 v[42:43], 1, v[42:43]
	v_lshlrev_b32_e32 v46, 16, v75
	v_and_b32_e32 v47, 0xffff0000, v75
	v_pk_fma_f32 v[44:45], v[22:23], v[142:143], v[44:45]
	v_pk_fma_f32 v[50:51], v[20:21], v[140:141], v[50:51]
	v_pk_fma_f32 v[48:49], v[18:19], v[138:139], v[48:49]
	v_lshl_add_u64 v[22:23], s[10:11], 0, v[42:43]
	v_or_b32_e32 v42, 0x100, v42
	v_pk_fma_f32 v[46:47], v[24:25], v[144:145], v[46:47]
	v_lshl_add_u64 v[24:25], s[0:1], 0, v[42:43]
	s_waitcnt lgkmcnt(0)
	v_pk_mul_f32 v[20:21], v[36:37], v[28:29]
	v_pk_mul_f32 v[18:19], v[34:35], v[26:27]
	s_waitcnt lgkmcnt(0)
; __device__ __forceinline__ void unpack8(const v4u w, float (&o)[8]) { o[0] = bflo(w.x); o[1] = bfhi(w.x); o[2] = bflo(w.y); o[3] = bfhi(w.y); o[4] = bflo(w.z); o[5] = bfhi(w.z); o[6] = bflo(w.w); o[7] = bfhi(w.w); }
; __device__ __forceinline__ unsigned cvt_pk_bf16(float lo, float hi) { unsigned r; asm volatile("v_cvt_pk_bf16_f32 %0, %1, %2" : "=v"(r) : "v"(lo), "v"(hi)); return r; }
;     template <int AI> __device__ __forceinline__ void half_rows(AccT acc, int row0, int col0, int slot, int sq, int fq, const f32x4 (&gsc)[4]) const {
;     ...
;         for (int m = 0; m < 4; ++m) { const int row = row0 + m * 16;
;             float ss = 0.f;
; #pragma unroll
;             for (int bj = 0; bj < 2; ++bj) { const size_t off = (size_t)row * DM + col0 + bj * HALF;
;                 float xi[8]; unpack8(xw[m][bj], xi);
;                 const f32x4 x0 = (f32x4){xi[0], xi[1], xi[2], xi[3]} + gsc[bj * 2] * acc[AI][bj][m][0], x1 = (f32x4){xi[4], xi[5], xi[6], xi[7]} + gsc[bj * 2 + 1] * acc[AI][bj][m][1];
;                 { u32x4 xs_; xs_.x = cvt_pk_bf16(x0[0], x0[1]); xs_.y = cvt_pk_bf16(x0[2], x0[3]); xs_.z = cvt_pk_bf16(x1[0], x1[1]); xs_.w = cvt_pk_bf16(x1[2], x1[3]); *(u32x4*)(X + off) = xs_; }
;                 if (NEXT) { ss += ((x0.x * x0.x + x0.y * x0.y) + (x0.z * x0.z + x0.w * x0.w)) + ((x1.x * x1.x + x1.y * x1.y) + (x1.z * x1.z + x1.w * x1.w));
;                     const float* gp_ = gam + (size_t)sq * DM + col0 + bj * HALF; const f32x4 y0 = x0 * *(const f32x4*)gp_, y1 = x1 * *(const f32x4*)(gp_ + 4);
;                     u32x4 w; w.x = cvt_pk_bf16(y0[0], y0[1]); w.y = cvt_pk_bf16(y0[2], y0[3]); w.z = cvt_pk_bf16(y1[0], y1[1]); w.w = cvt_pk_bf16(y1[2], y1[3]);
;                     *(u32x4*)(XB + off) = w; } }
;             if (NEXT) { ss += __shfl_xor(ss, 16); ss += __shfl_xor(ss, 32); if (fq == 0) SSQ[(size_t)row * 16 + slot] = ss; } }
	v_pk_mul_f32 v[26:27], v[40:41], v[32:33]
	v_pk_mul_f32 v[28:29], v[38:39], v[30:31]
	v_cvt_pk_bf16_f32 v18, v18, v19
	v_cvt_pk_bf16_f32 v19, v20, v21
	v_mul_f32_e32 v30, v45, v45
	v_cvt_pk_bf16_f32 v20, v28, v29
	v_cvt_pk_bf16_f32 v21, v26, v27
	global_store_dwordx4 v[22:23], v[18:21], off
	v_mul_f32_e32 v28, v39, v39
	v_mul_f32_e32 v29, v41, v41
	v_cvt_pk_bf16_f32 v18, v44, v45
	v_cvt_pk_bf16_f32 v19, v46, v47
	v_cvt_pk_bf16_f32 v20, v48, v49
	v_cvt_pk_bf16_f32 v21, v50, v51
	global_store_dwordx4 v[24:25], v[18:21], off
	ds_read_b128 v[20:23], v255 offset:32
	s_nop 0
	ds_read_b128 v[24:27], v255 offset:48
	v_mul_f32_e32 v18, v35, v35
	v_mul_f32_e32 v19, v37, v37
	v_mul_f32_e32 v31, v47, v47
	v_mul_f32_e32 v32, v49, v49
	v_mul_f32_e32 v33, v51, v51
	v_fmac_f32_e32 v18, v34, v34
	v_fmac_f32_e32 v19, v36, v36
	v_fmac_f32_e32 v28, v38, v38
	v_fmac_f32_e32 v29, v40, v40
	v_fmac_f32_e32 v30, v44, v44
	v_fmac_f32_e32 v31, v46, v46
	v_fmac_f32_e32 v32, v48, v48
	v_fmac_f32_e32 v33, v50, v50
	v_add_f32_e32 v18, v18, v19
	v_add_f32_e32 v19, v28, v29
	v_add_f32_e32 v28, v30, v31
	v_add_f32_e32 v29, v32, v33
	v_add_f32_e32 v18, v18, v19
	v_add_f32_e32 v19, v28, v29
	v_add_f32_e32 v18, v18, v19
	ds_bpermute_b32 v19, v126, v18
	s_waitcnt lgkmcnt(0)
	v_add_f32_e32 v18, v18, v19
	ds_bpermute_b32 v19, v127, v18
	s_waitcnt lgkmcnt(0)
	v_pk_mul_f32 v[22:23], v[46:47], v[22:23]
	v_pk_mul_f32 v[20:21], v[44:45], v[20:21]
	s_waitcnt lgkmcnt(0)
	v_pk_mul_f32 v[24:25], v[48:49], v[24:25]
	v_cvt_pk_bf16_f32 v20, v20, v21
	v_cvt_pk_bf16_f32 v21, v22, v23
	v_pk_mul_f32 v[26:27], v[50:51], v[26:27]
	v_cvt_pk_bf16_f32 v22, v24, v25
	v_lshl_add_u64 v[24:25], s[10:11], 0, v[42:43]
	v_cvt_pk_bf16_f32 v23, v26, v27
	global_store_dwordx4 v[24:25], v[20:23], off
	s_and_saveexec_b64 s[30:31], s[4:5]
	s_cbranch_execz .LBB0_571
	v_lshlrev_b64 v[20:21], 6, v[94:95]
	v_lshl_add_u64 v[20:21], s[12:13], 0, v[20:21]
	v_lshl_add_u64 v[20:21], s[28:29], 2, v[20:21]
	s_waitcnt lgkmcnt(0)
	v_add_f32_e32 v18, v18, v19
	global_store_dword v[20:21], v18, off
.LBB0_571:
	s_or_b64 exec, exec, s[30:31]
	v_lshlrev_b32_e32 v18, 16, v70
	s_waitcnt lgkmcnt(0)
	v_and_b32_e32 v19, 0xffff0000, v70
	v_lshlrev_b32_e32 v20, 16, v71
	v_and_b32_e32 v21, 0xffff0000, v71
	v_lshlrev_b32_e32 v22, 16, v72
	v_and_b32_e32 v23, 0xffff0000, v72
	v_lshlrev_b32_e32 v24, 16, v73
	v_and_b32_e32 v25, 0xffff0000, v73
	v_pk_fma_f32 v[20:21], v[16:17], v[180:181], v[20:21]
	v_pk_fma_f32 v[18:19], v[14:15], v[178:179], v[18:19]
	v_pk_fma_f32 v[24:25], v[12:13], v[176:177], v[24:25]
	v_pk_fma_f32 v[22:23], v[10:11], v[174:175], v[22:23]
	v_cvt_pk_bf16_f32 v10, v18, v19
	v_cvt_pk_bf16_f32 v11, v20, v21
	v_lshlrev_b64 v[26:27], 10, v[90:91]
	v_cvt_pk_bf16_f32 v12, v22, v23
	v_cvt_pk_bf16_f32 v13, v24, v25
	global_store_dwordx4 v[92:93], v[10:13], off
	ds_read_b128 v[10:13], v255
	s_nop 0
	ds_read_b128 v[14:17], v255 offset:16
	v_lshl_add_u64 v[26:27], v[26:27], 0, v[170:171]
	v_lshlrev_b32_e32 v28, 16, v66
	v_and_b32_e32 v29, 0xffff0000, v66
	v_lshlrev_b32_e32 v32, 16, v68
	v_and_b32_e32 v33, 0xffff0000, v68
	v_lshlrev_b32_e32 v34, 16, v69
	v_and_b32_e32 v35, 0xffff0000, v69
	v_lshlrev_b64 v[26:27], 1, v[26:27]
	v_lshlrev_b32_e32 v30, 16, v67
	v_and_b32_e32 v31, 0xffff0000, v67
	v_pk_fma_f32 v[28:29], v[6:7], v[142:143], v[28:29]
	v_pk_fma_f32 v[34:35], v[4:5], v[140:141], v[34:35]
	v_pk_fma_f32 v[32:33], v[2:3], v[138:139], v[32:33]
	v_lshl_add_u64 v[6:7], s[10:11], 0, v[26:27]
	v_or_b32_e32 v26, 0x100, v26
	v_pk_fma_f32 v[30:31], v[8:9], v[144:145], v[30:31]
	v_lshl_add_u64 v[8:9], s[0:1], 0, v[26:27]
	s_waitcnt lgkmcnt(0)
	v_pk_mul_f32 v[4:5], v[20:21], v[12:13]
	v_pk_mul_f32 v[2:3], v[18:19], v[10:11]
	s_waitcnt lgkmcnt(0)
	v_pk_mul_f32 v[10:11], v[24:25], v[16:17]
	v_pk_mul_f32 v[12:13], v[22:23], v[14:15]
	v_cvt_pk_bf16_f32 v2, v2, v3
	v_cvt_pk_bf16_f32 v3, v4, v5
	v_mul_f32_e32 v14, v29, v29
	v_cvt_pk_bf16_f32 v4, v12, v13
	v_cvt_pk_bf16_f32 v5, v10, v11
	global_store_dwordx4 v[6:7], v[2:5], off
	v_mul_f32_e32 v12, v23, v23
	v_mul_f32_e32 v13, v25, v25
	v_cvt_pk_bf16_f32 v2, v28, v29
	v_cvt_pk_bf16_f32 v3, v30, v31
	v_cvt_pk_bf16_f32 v4, v32, v33
	v_cvt_pk_bf16_f32 v5, v34, v35
	global_store_dwordx4 v[8:9], v[2:5], off
	ds_read_b128 v[4:7], v255 offset:32
	s_nop 0
	ds_read_b128 v[8:11], v255 offset:48
	v_mul_f32_e32 v2, v19, v19
	v_mul_f32_e32 v3, v21, v21
	v_mul_f32_e32 v15, v31, v31
	v_mul_f32_e32 v16, v33, v33
	v_mul_f32_e32 v17, v35, v35
	v_fmac_f32_e32 v2, v18, v18
	v_fmac_f32_e32 v3, v20, v20
	v_fmac_f32_e32 v12, v22, v22
	v_fmac_f32_e32 v13, v24, v24
	v_fmac_f32_e32 v14, v28, v28
	v_fmac_f32_e32 v15, v30, v30
	v_fmac_f32_e32 v16, v32, v32
	v_fmac_f32_e32 v17, v34, v34
	v_add_f32_e32 v2, v2, v3
	v_add_f32_e32 v3, v12, v13
	v_add_f32_e32 v12, v14, v15
	v_add_f32_e32 v13, v16, v17
	v_add_f32_e32 v2, v2, v3
	v_add_f32_e32 v3, v12, v13
	v_add_f32_e32 v2, v2, v3
	ds_bpermute_b32 v3, v126, v2
	s_waitcnt lgkmcnt(0)
	v_add_f32_e32 v2, v2, v3
	ds_bpermute_b32 v3, v127, v2
	s_waitcnt lgkmcnt(0)
	v_pk_mul_f32 v[6:7], v[30:31], v[6:7]
	v_pk_mul_f32 v[4:5], v[28:29], v[4:5]
	s_waitcnt lgkmcnt(0)
	v_pk_mul_f32 v[8:9], v[32:33], v[8:9]
	v_cvt_pk_bf16_f32 v4, v4, v5
	v_cvt_pk_bf16_f32 v5, v6, v7
	v_pk_mul_f32 v[10:11], v[34:35], v[10:11]
	v_cvt_pk_bf16_f32 v6, v8, v9
	v_lshl_add_u64 v[8:9], s[10:11], 0, v[26:27]
	v_cvt_pk_bf16_f32 v7, v10, v11
	global_store_dwordx4 v[8:9], v[4:7], off
	s_and_saveexec_b64 s[30:31], s[4:5]
	s_cbranch_execz .LBB0_573
	v_lshlrev_b64 v[4:5], 6, v[90:91]
	v_lshl_add_u64 v[4:5], s[12:13], 0, v[4:5]
	v_lshl_add_u64 v[4:5], s[28:29], 2, v[4:5]
	s_waitcnt lgkmcnt(0)
	v_add_f32_e32 v2, v2, v3
	global_store_dword v[4:5], v2, off

;     template <int AI> __device__ __forceinline__ void half_rows(AccT acc, int row0, int col0, int slot, int sq, int fq, const f32x4 (&gsc)[4]) const {
;         v4u xw[4][2];
; #pragma unroll
;         for (int m = 0; m < 4; ++m)
; #pragma unroll
;             for (int bj = 0; bj < 2; ++bj) xw[m][bj] = *(const v4u*)(X + (size_t)(row0 + m * 16) * DM + col0 + bj * HALF);
; #pragma unroll
;         for (int m = 0; m < 4; ++m) { const int row = row0 + m * 16;
;             float ss = 0.f;
; #pragma unroll
;             for (int bj = 0; bj < 2; ++bj) { const size_t off = (size_t)row * DM + col0 + bj * HALF;
;                 float xi[8]; unpack8(xw[m][bj], xi);
;                 const f32x4 x0 = (f32x4){xi[0], xi[1], xi[2], xi[3]} + gsc[bj * 2] * acc[AI][bj][m][0], x1 = (f32x4){xi[4], xi[5], xi[6], xi[7]} + gsc[bj * 2 + 1] * acc[AI][bj][m][1];
;                 { u32x4 xs_; xs_.x = cvt_pk_bf16(x0[0], x0[1]); xs_.y = cvt_pk_bf16(x0[2], x0[3]); xs_.z = cvt_pk_bf16(x1[0], x1[1]); xs_.w = cvt_pk_bf16(x1[2], x1[3]); *(u32x4*)(X + off) = xs_; }
;                 if (NEXT) { ss += ((x0.x * x0.x + x0.y * x0.y) + (x0.z * x0.z + x0.w * x0.w)) + ((x1.x * x1.x + x1.y * x1.y) + (x1.z * x1.z + x1.w * x1.w));
;                     const float* gp_ = gam + (size_t)sq * DM + col0 + bj * HALF; const f32x4 y0 = x0 * *(const f32x4*)gp_, y1 = x1 * *(const f32x4*)(gp_ + 4);
;                     u32x4 w; w.x = cvt_pk_bf16(y0[0], y0[1]); w.y = cvt_pk_bf16(y0[2], y0[3]); w.z = cvt_pk_bf16(y1[0], y1[1]); w.w = cvt_pk_bf16(y1[2], y1[3]);
;                     *(u32x4*)(XB + off) = w; } }
;             if (NEXT) { ss += __shfl_xor(ss, 16); ss += __shfl_xor(ss, 32); if (fq == 0) SSQ[(size_t)row * 16 + slot] = ss; } }
;     }
;     __device__ __forceinline__ void operator()(AccT acc, const Unit& u, int wr, int wc, int fr, int fq) const {
;         const int upm = u.pm, upn = u.pn, uhalf = u.half;
;         const int col0 = upn * BM + wc * 32 + 8 * fq, sq = upm >> 3, slot = upn * 4 + wc, rbase = upm * BM + wr * 64 + fr;
;         f32x4 gsc[4];
; #pragma unroll
;         for (int q = 0; q < 4; ++q) gsc[q] = *(const f32x4*)(gate + (size_t)sq * NMOD + col0 + (q >> 1) * HALF + 4 * (q & 1)) * scale;
;         if (uhalf != 1) half_rows<0>(acc, rbase, col0, slot, sq, fq, gsc);
;         if (uhalf != 0) half_rows<1>(acc, rbase + HALF, col0, slot, sq, fq, gsc);
.LBB0_2136:
	v_lshl_or_b32 v186, s36, 8, v206
	s_ashr_i32 s38, s34, 3
	v_lshl_add_u32 v192, s34, 8, v1
	s_lshl_b32 s25, s36, 2
	v_ashrrev_i32_e32 v187, 31, v186
	v_ashrrev_i32_e32 v193, 31, v192
	s_ashr_i32 s39, s38, 31
	s_mul_i32 s34, s38, 0x9000
	v_lshl_add_u64 v[190:191], v[186:187], 1, s[0:1]
	v_lshlrev_b64 v[34:35], 11, v[192:193]
	s_mul_hi_i32 s27, s38, 0x9000
	s_add_u32 s34, s12, s34
	v_lshl_add_u64 v[222:223], v[190:191], 0, v[34:35]
	s_addc_u32 s35, s13, s27
	v_lshlrev_b64 v[188:189], 2, v[186:187]
	global_load_dwordx4 v[214:217], v[222:223], off
	v_lshl_add_u64 v[38:39], s[34:35], 0, v[188:189]
	global_load_dwordx4 v[46:49], v[38:39], off
	global_load_dwordx4 v[42:45], v[38:39], off offset:16
	s_or_b32 s34, s25, s56
	v_or_b32_e32 v202, 16, v192
	v_or_b32_e32 v198, 32, v192
	v_or_b32_e32 v194, 48, v192
	s_lshl_b64 s[36:37], s[38:39], 12
	s_ashr_i32 s35, s34, 31
	v_ashrrev_i32_e32 v203, 31, v202
	v_ashrrev_i32_e32 v199, 31, v198
	v_ashrrev_i32_e32 v195, 31, v194
	s_add_u32 s36, s14, s36
	v_lshlrev_b64 v[34:35], 11, v[202:203]
	v_lshlrev_b64 v[36:37], 11, v[198:199]
	v_lshlrev_b64 v[40:41], 11, v[194:195]
	global_load_dwordx4 v[218:221], v[222:223], off offset:256
	s_addc_u32 s37, s15, s37
	v_lshl_add_u64 v[204:205], v[190:191], 0, v[34:35]
	v_lshl_add_u64 v[200:201], v[190:191], 0, v[36:37]
	v_lshl_add_u64 v[196:197], v[190:191], 0, v[40:41]
	global_load_dwordx4 v[34:37], v[38:39], off offset:528
	s_nop 0
	global_load_dwordx4 v[38:41], v[38:39], off offset:512
	s_nop 0
	global_load_dwordx4 v[166:169], v[204:205], off
	global_load_dwordx4 v[162:165], v[204:205], off offset:256
	global_load_dwordx4 v[150:153], v[200:201], off
	global_load_dwordx4 v[138:141], v[200:201], off offset:256
	global_load_dwordx4 v[126:129], v[196:197], off
	global_load_dwordx4 v[114:117], v[196:197], off offset:256
	v_lshl_add_u64 v[188:189], s[36:37], 0, v[188:189]
	global_load_dwordx4 v[244:247], v[188:189], off
	global_load_dwordx4 v[248:251], v[188:189], off offset:16
	v_lshrrev_b32_e32 v255, 6, v0
	v_lshlrev_b32_e32 v255, 8, v255
	v_bfe_u32 v252, v0, 4, 2
	v_lshl_add_u32 v255, v252, 6, v255
	v_add_u32_e32 v255, 0x20000, v255
	s_waitcnt vmcnt(0)
	ds_write_b128 v255, v[244:247]
	ds_write_b128 v255, v[248:251] offset:16
	global_load_dwordx4 v[244:247], v[188:189], off offset:512
	global_load_dwordx4 v[248:251], v[188:189], off offset:528
	s_waitcnt vmcnt(0)
	ds_write_b128 v255, v[244:247] offset:32
	ds_write_b128 v255, v[248:251] offset:48
	s_waitcnt lgkmcnt(0)
	v_lshlrev_b32_e32 v224, 16, v214
	v_and_b32_e32 v225, 0xffff0000, v214
	v_lshlrev_b32_e32 v214, 16, v215
	v_and_b32_e32 v215, 0xffff0000, v215
	v_lshlrev_b32_e32 v226, 16, v216
	v_and_b32_e32 v227, 0xffff0000, v216
	v_lshlrev_b32_e32 v216, 16, v217
	v_and_b32_e32 v217, 0xffff0000, v217
	v_pk_fma_f32 v[214:215], v[160:161], v[48:49], v[214:215]
	v_pk_fma_f32 v[224:225], v[158:159], v[46:47], v[224:225]
	v_pk_fma_f32 v[216:217], v[156:157], v[44:45], v[216:217]
	v_pk_fma_f32 v[226:227], v[154:155], v[42:43], v[226:227]
	v_cvt_pk_bf16_f32 v154, v224, v225
	v_cvt_pk_bf16_f32 v155, v214, v215
	v_lshlrev_b32_e32 v234, 16, v220
	v_cvt_pk_bf16_f32 v156, v226, v227
	v_cvt_pk_bf16_f32 v157, v216, v217
	global_store_dwordx4 v[222:223], v[154:157], off
	ds_read_b128 v[154:157], v255
	s_nop 0
	ds_read_b128 v[158:161], v255 offset:16
	v_lshlrev_b64 v[222:223], 10, v[192:193]
	v_lshl_add_u64 v[222:223], v[222:223], 0, v[186:187]
	v_lshlrev_b64 v[222:223], 1, v[222:223]
	v_and_b32_e32 v235, 0xffff0000, v220
	v_lshlrev_b32_e32 v220, 16, v221
	v_and_b32_e32 v221, 0xffff0000, v221
	v_lshl_add_u64 v[228:229], s[8:9], 0, v[222:223]
	v_or_b32_e32 v222, 0x100, v222
	v_lshlrev_b32_e32 v232, 16, v218
	v_and_b32_e32 v233, 0xffff0000, v218
	v_lshlrev_b32_e32 v218, 16, v219
	v_and_b32_e32 v219, 0xffff0000, v219
	v_pk_fma_f32 v[220:221], v[144:145], v[36:37], v[220:221]
	v_pk_fma_f32 v[234:235], v[142:143], v[34:35], v[234:235]
	v_lshl_add_u64 v[230:231], s[0:1], 0, v[222:223]
	v_pk_fma_f32 v[218:219], v[148:149], v[40:41], v[218:219]
	v_pk_fma_f32 v[232:233], v[146:147], v[38:39], v[232:233]
	v_mul_f32_e32 v213, v235, v235
	v_fmac_f32_e32 v213, v234, v234
	s_waitcnt lgkmcnt(0)
	v_pk_mul_f32 v[144:145], v[214:215], v[156:157]
	v_pk_mul_f32 v[142:143], v[224:225], v[154:155]
	s_waitcnt lgkmcnt(0)
	v_pk_mul_f32 v[146:147], v[216:217], v[160:161]
	v_pk_mul_f32 v[148:149], v[226:227], v[158:159]
	v_cvt_pk_bf16_f32 v142, v142, v143
	v_cvt_pk_bf16_f32 v143, v144, v145
	v_mul_f32_e32 v158, v227, v227
	v_cvt_pk_bf16_f32 v144, v148, v149
	v_cvt_pk_bf16_f32 v145, v146, v147
	global_store_dwordx4 v[228:229], v[142:145], off
	v_mul_f32_e32 v159, v217, v217
	v_mul_f32_e32 v160, v233, v233
	v_cvt_pk_bf16_f32 v142, v232, v233
	v_cvt_pk_bf16_f32 v143, v218, v219
	v_cvt_pk_bf16_f32 v144, v234, v235
	v_cvt_pk_bf16_f32 v145, v220, v221
	global_store_dwordx4 v[230:231], v[142:145], off
	ds_read_b128 v[146:149], v255 offset:32
	ds_read_b128 v[154:157], v255 offset:48
	v_and_b32_e32 v143, 64, v212
	v_mul_f32_e32 v144, v225, v225
	v_mul_f32_e32 v145, v215, v215
	v_mul_f32_e32 v161, v219, v219
	v_mul_f32_e32 v215, v221, v221
	v_xor_b32_e32 v142, 16, v212
	v_add_u32_e32 v143, 64, v143
	v_fmac_f32_e32 v144, v224, v224
	v_fmac_f32_e32 v145, v214, v214
	v_fmac_f32_e32 v158, v226, v226
	v_fmac_f32_e32 v159, v216, v216
	v_fmac_f32_e32 v160, v232, v232
	v_fmac_f32_e32 v161, v218, v218
	v_fmac_f32_e32 v215, v220, v220
	v_cmp_lt_i32_e32 vcc, v142, v143
	v_add_f32_e32 v144, v144, v145
	v_add_f32_e32 v145, v158, v159
	v_add_f32_e32 v158, v160, v161
	v_add_f32_e32 v159, v213, v215
	v_cndmask_b32_e32 v142, v212, v142, vcc
	v_add_f32_e32 v144, v144, v145
	v_add_f32_e32 v145, v158, v159
	v_lshlrev_b32_e32 v142, 2, v142
	v_add_f32_e32 v144, v144, v145
	ds_bpermute_b32 v145, v142, v144
	v_xor_b32_e32 v158, 32, v212
	v_cmp_lt_i32_e32 vcc, v158, v143
	s_waitcnt lgkmcnt(0)
	v_add_f32_e32 v144, v144, v145
	v_cndmask_b32_e32 v143, v212, v158, vcc
	v_lshlrev_b32_e32 v143, 2, v143
	ds_bpermute_b32 v145, v143, v144
	s_waitcnt lgkmcnt(0)
	v_pk_mul_f32 v[148:149], v[218:219], v[148:149]
	v_pk_mul_f32 v[146:147], v[232:233], v[146:147]
	s_waitcnt lgkmcnt(0)
	v_pk_mul_f32 v[154:155], v[234:235], v[154:155]
	v_cvt_pk_bf16_f32 v146, v146, v147
	v_cvt_pk_bf16_f32 v147, v148, v149
	v_pk_mul_f32 v[156:157], v[220:221], v[156:157]
	v_cvt_pk_bf16_f32 v148, v154, v155
	v_lshl_add_u64 v[154:155], s[8:9], 0, v[222:223]
	v_cvt_pk_bf16_f32 v149, v156, v157
	global_store_dwordx4 v[154:155], v[146:149], off
	s_and_saveexec_b64 s[36:37], s[4:5]
	s_cbranch_execz .LBB0_2138
	v_lshlrev_b64 v[146:147], 6, v[192:193]
	v_lshl_add_u64 v[146:147], s[10:11], 0, v[146:147]
	v_lshl_add_u64 v[146:147], s[34:35], 2, v[146:147]
	s_waitcnt lgkmcnt(0)
	v_add_f32_e32 v144, v144, v145
	global_store_dword v[146:147], v144, off
; __device__ __forceinline__ void unpack8(const v4u w, float (&o)[8]) { o[0] = bflo(w.x); o[1] = bfhi(w.x); o[2] = bflo(w.y); o[3] = bfhi(w.y); o[4] = bflo(w.z); o[5] = bfhi(w.z); o[6] = bflo(w.w); o[7] = bfhi(w.w); }
; __device__ __forceinline__ unsigned cvt_pk_bf16(float lo, float hi) { unsigned r; asm volatile("v_cvt_pk_bf16_f32 %0, %1, %2" : "=v"(r) : "v"(lo), "v"(hi)); return r; }
;     template <int AI> __device__ __forceinline__ void half_rows(AccT acc, int row0, int col0, int slot, int sq, int fq, const f32x4 (&gsc)[4]) const {
;     ...
;         for (int m = 0; m < 4; ++m) { const int row = row0 + m * 16;
;             float ss = 0.f;
; #pragma unroll
;             for (int bj = 0; bj < 2; ++bj) { const size_t off = (size_t)row * DM + col0 + bj * HALF;
;                 float xi[8]; unpack8(xw[m][bj], xi);
;                 const f32x4 x0 = (f32x4){xi[0], xi[1], xi[2], xi[3]} + gsc[bj * 2] * acc[AI][bj][m][0], x1 = (f32x4){xi[4], xi[5], xi[6], xi[7]} + gsc[bj * 2 + 1] * acc[AI][bj][m][1];
;                 { u32x4 xs_; xs_.x = cvt_pk_bf16(x0[0], x0[1]); xs_.y = cvt_pk_bf16(x0[2], x0[3]); xs_.z = cvt_pk_bf16(x1[0], x1[1]); xs_.w = cvt_pk_bf16(x1[2], x1[3]); *(u32x4*)(X + off) = xs_; }
;                 if (NEXT) { ss += ((x0.x * x0.x + x0.y * x0.y) + (x0.z * x0.z + x0.w * x0.w)) + ((x1.x * x1.x + x1.y * x1.y) + (x1.z * x1.z + x1.w * x1.w));
;                     const float* gp_ = gam + (size_t)sq * DM + col0 + bj * HALF; const f32x4 y0 = x0 * *(const f32x4*)gp_, y1 = x1 * *(const f32x4*)(gp_ + 4);
;                     u32x4 w; w.x = cvt_pk_bf16(y0[0], y0[1]); w.y = cvt_pk_bf16(y0[2], y0[3]); w.z = cvt_pk_bf16(y1[0], y1[1]); w.w = cvt_pk_bf16(y1[2], y1[3]);
;                     *(u32x4*)(XB + off) = w; } }
;             if (NEXT) { ss += __shfl_xor(ss, 16); ss += __shfl_xor(ss, 32); if (fq == 0) SSQ[(size_t)row * 16 + slot] = ss; } }
.LBB0_2138:
	s_or_b64 exec, exec, s[36:37]
	v_lshlrev_b32_e32 v144, 16, v166
	s_waitcnt lgkmcnt(0)
	v_and_b32_e32 v145, 0xffff0000, v166
	v_lshlrev_b32_e32 v146, 16, v167
	v_and_b32_e32 v147, 0xffff0000, v167
	v_lshlrev_b32_e32 v148, 16, v168
	v_and_b32_e32 v149, 0xffff0000, v168
	v_lshlrev_b32_e32 v154, 16, v169
	v_and_b32_e32 v155, 0xffff0000, v169
	v_pk_fma_f32 v[146:147], v[136:137], v[48:49], v[146:147]
	v_pk_fma_f32 v[144:145], v[134:135], v[46:47], v[144:145]
	v_pk_fma_f32 v[154:155], v[132:133], v[44:45], v[154:155]
	v_pk_fma_f32 v[148:149], v[130:131], v[42:43], v[148:149]
	v_cvt_pk_bf16_f32 v130, v144, v145
	v_cvt_pk_bf16_f32 v131, v146, v147
	v_lshlrev_b64 v[156:157], 10, v[202:203]
	v_cvt_pk_bf16_f32 v132, v148, v149
	v_cvt_pk_bf16_f32 v133, v154, v155
	global_store_dwordx4 v[204:205], v[130:133], off
	ds_read_b128 v[130:133], v255
	s_nop 0
	ds_read_b128 v[134:137], v255 offset:16
	v_lshl_add_u64 v[156:157], v[156:157], 0, v[186:187]
	v_lshlrev_b32_e32 v158, 16, v162
	v_and_b32_e32 v159, 0xffff0000, v162
	v_lshlrev_b32_e32 v160, 16, v163
	v_and_b32_e32 v161, 0xffff0000, v163
	v_lshlrev_b32_e32 v162, 16, v164
	v_and_b32_e32 v163, 0xffff0000, v164
	v_lshlrev_b32_e32 v164, 16, v165
	v_and_b32_e32 v165, 0xffff0000, v165
	v_lshlrev_b64 v[156:157], 1, v[156:157]
	v_pk_fma_f32 v[124:125], v[124:125], v[40:41], v[160:161]
	v_pk_fma_f32 v[158:159], v[122:123], v[38:39], v[158:159]
	v_pk_fma_f32 v[160:161], v[120:121], v[36:37], v[164:165]
	v_pk_fma_f32 v[162:163], v[118:119], v[34:35], v[162:163]
	v_lshl_add_u64 v[122:123], s[8:9], 0, v[156:157]
	v_or_b32_e32 v156, 0x100, v156
	v_lshl_add_u64 v[164:165], s[0:1], 0, v[156:157]
	s_waitcnt lgkmcnt(0)
	v_pk_mul_f32 v[120:121], v[146:147], v[132:133]
	v_pk_mul_f32 v[118:119], v[144:145], v[130:131]
	s_waitcnt lgkmcnt(0)
	v_pk_mul_f32 v[130:131], v[154:155], v[136:137]
	v_pk_mul_f32 v[132:133], v[148:149], v[134:135]
	v_cvt_pk_bf16_f32 v118, v118, v119
	v_cvt_pk_bf16_f32 v119, v120, v121
	v_mul_f32_e32 v134, v149, v149
	v_cvt_pk_bf16_f32 v120, v132, v133
	v_cvt_pk_bf16_f32 v121, v130, v131
	global_store_dwordx4 v[122:123], v[118:121], off
	v_mul_f32_e32 v135, v155, v155
	v_mul_f32_e32 v136, v159, v159
	v_cvt_pk_bf16_f32 v118, v158, v159
	v_cvt_pk_bf16_f32 v119, v124, v125
	v_cvt_pk_bf16_f32 v120, v162, v163
	v_cvt_pk_bf16_f32 v121, v160, v161
	global_store_dwordx4 v[164:165], v[118:121], off
	ds_read_b128 v[120:123], v255 offset:32
	s_nop 0
	ds_read_b128 v[130:133], v255 offset:48
	v_mul_f32_e32 v118, v145, v145
	v_mul_f32_e32 v119, v147, v147
	v_mul_f32_e32 v137, v125, v125
	v_mul_f32_e32 v145, v163, v163
	v_mul_f32_e32 v147, v161, v161
	v_fmac_f32_e32 v118, v144, v144
	v_fmac_f32_e32 v119, v146, v146
	v_fmac_f32_e32 v134, v148, v148
	v_fmac_f32_e32 v135, v154, v154
	v_fmac_f32_e32 v136, v158, v158
	v_fmac_f32_e32 v137, v124, v124
	v_fmac_f32_e32 v145, v162, v162
	v_fmac_f32_e32 v147, v160, v160
	v_add_f32_e32 v118, v118, v119
	v_add_f32_e32 v119, v134, v135
	v_add_f32_e32 v134, v136, v137
	v_add_f32_e32 v135, v145, v147
	v_add_f32_e32 v118, v118, v119
	v_add_f32_e32 v119, v134, v135
	v_add_f32_e32 v118, v118, v119
	ds_bpermute_b32 v119, v142, v118
	s_waitcnt lgkmcnt(0)
	v_add_f32_e32 v118, v118, v119
	ds_bpermute_b32 v119, v143, v118
	s_waitcnt lgkmcnt(0)
	v_pk_mul_f32 v[122:123], v[124:125], v[122:123]
	v_pk_mul_f32 v[120:121], v[158:159], v[120:121]
	s_waitcnt lgkmcnt(0)
	v_pk_mul_f32 v[124:125], v[160:161], v[132:133]
	v_pk_mul_f32 v[130:131], v[162:163], v[130:131]
	v_cvt_pk_bf16_f32 v120, v120, v121
	v_cvt_pk_bf16_f32 v121, v122, v123
	s_nop 0
	v_cvt_pk_bf16_f32 v122, v130, v131
	v_cvt_pk_bf16_f32 v123, v124, v125
	v_lshl_add_u64 v[124:125], s[8:9], 0, v[156:157]
	global_store_dwordx4 v[124:125], v[120:123], off
	s_and_saveexec_b64 s[36:37], s[4:5]
	s_cbranch_execz .LBB0_2140
	v_lshlrev_b64 v[120:121], 6, v[202:203]
	v_lshl_add_u64 v[120:121], s[10:11], 0, v[120:121]
	v_lshl_add_u64 v[120:121], s[34:35], 2, v[120:121]
	s_waitcnt lgkmcnt(0)
	v_add_f32_e32 v118, v118, v119
	global_store_dword v[120:121], v118, off
.LBB0_2140:
	s_or_b64 exec, exec, s[36:37]
	v_lshlrev_b32_e32 v118, 16, v150
	s_waitcnt lgkmcnt(0)
	v_and_b32_e32 v119, 0xffff0000, v150
	v_lshlrev_b32_e32 v120, 16, v151
	v_and_b32_e32 v121, 0xffff0000, v151
	v_lshlrev_b32_e32 v122, 16, v152
	v_and_b32_e32 v123, 0xffff0000, v152
	v_lshlrev_b32_e32 v124, 16, v153
	v_and_b32_e32 v125, 0xffff0000, v153
	v_pk_fma_f32 v[120:121], v[112:113], v[48:49], v[120:121]
	v_pk_fma_f32 v[118:119], v[110:111], v[46:47], v[118:119]
	v_pk_fma_f32 v[124:125], v[108:109], v[44:45], v[124:125]
	v_pk_fma_f32 v[122:123], v[106:107], v[42:43], v[122:123]
	v_cvt_pk_bf16_f32 v106, v118, v119
	v_cvt_pk_bf16_f32 v107, v120, v121
	v_lshlrev_b64 v[130:131], 10, v[198:199]
	v_cvt_pk_bf16_f32 v108, v122, v123
	v_cvt_pk_bf16_f32 v109, v124, v125
	global_store_dwordx4 v[200:201], v[106:109], off
	ds_read_b128 v[106:109], v255
	s_nop 0
	ds_read_b128 v[110:113], v255 offset:16
	v_lshl_add_u64 v[130:131], v[130:131], 0, v[186:187]
	v_lshlrev_b32_e32 v132, 16, v138
	v_and_b32_e32 v133, 0xffff0000, v138
	v_lshlrev_b32_e32 v134, 16, v139
	v_and_b32_e32 v135, 0xffff0000, v139
	v_lshlrev_b32_e32 v136, 16, v140
	v_and_b32_e32 v137, 0xffff0000, v140
	v_lshlrev_b32_e32 v138, 16, v141
	v_and_b32_e32 v139, 0xffff0000, v141
	v_lshlrev_b64 v[130:131], 1, v[130:131]
	v_pk_fma_f32 v[132:133], v[102:103], v[38:39], v[132:133]
	v_pk_fma_f32 v[138:139], v[100:101], v[36:37], v[138:139]
	v_pk_fma_f32 v[136:137], v[98:99], v[34:35], v[136:137]
	v_lshl_add_u64 v[102:103], s[8:9], 0, v[130:131]
	v_or_b32_e32 v130, 0x100, v130
	v_pk_fma_f32 v[134:135], v[104:105], v[40:41], v[134:135]
	v_lshl_add_u64 v[104:105], s[0:1], 0, v[130:131]
	s_waitcnt lgkmcnt(0)
; __device__ __forceinline__ void unpack8(const v4u w, float (&o)[8]) { o[0] = bflo(w.x); o[1] = bfhi(w.x); o[2] = bflo(w.y); o[3] = bfhi(w.y); o[4] = bflo(w.z); o[5] = bfhi(w.z); o[6] = bflo(w.w); o[7] = bfhi(w.w); }
; __device__ __forceinline__ unsigned cvt_pk_bf16(float lo, float hi) { unsigned r; asm volatile("v_cvt_pk_bf16_f32 %0, %1, %2" : "=v"(r) : "v"(lo), "v"(hi)); return r; }
;     template <int AI> __device__ __forceinline__ void half_rows(AccT acc, int row0, int col0, int slot, int sq, int fq, const f32x4 (&gsc)[4]) const {
;     ...
;         for (int m = 0; m < 4; ++m) { const int row = row0 + m * 16;
;             float ss = 0.f;
; #pragma unroll
;             for (int bj = 0; bj < 2; ++bj) { const size_t off = (size_t)row * DM + col0 + bj * HALF;
;                 float xi[8]; unpack8(xw[m][bj], xi);
;                 const f32x4 x0 = (f32x4){xi[0], xi[1], xi[2], xi[3]} + gsc[bj * 2] * acc[AI][bj][m][0], x1 = (f32x4){xi[4], xi[5], xi[6], xi[7]} + gsc[bj * 2 + 1] * acc[AI][bj][m][1];
;                 { u32x4 xs_; xs_.x = cvt_pk_bf16(x0[0], x0[1]); xs_.y = cvt_pk_bf16(x0[2], x0[3]); xs_.z = cvt_pk_bf16(x1[0], x1[1]); xs_.w = cvt_pk_bf16(x1[2], x1[3]); *(u32x4*)(X + off) = xs_; }
;                 if (NEXT) { ss += ((x0.x * x0.x + x0.y * x0.y) + (x0.z * x0.z + x0.w * x0.w)) + ((x1.x * x1.x + x1.y * x1.y) + (x1.z * x1.z + x1.w * x1.w));
;                     const float* gp_ = gam + (size_t)sq * DM + col0 + bj * HALF; const f32x4 y0 = x0 * *(const f32x4*)gp_, y1 = x1 * *(const f32x4*)(gp_ + 4);
;                     u32x4 w; w.x = cvt_pk_bf16(y0[0], y0[1]); w.y = cvt_pk_bf16(y0[2], y0[3]); w.z = cvt_pk_bf16(y1[0], y1[1]); w.w = cvt_pk_bf16(y1[2], y1[3]);
;                     *(u32x4*)(XB + off) = w; } }
;             if (NEXT) { ss += __shfl_xor(ss, 16); ss += __shfl_xor(ss, 32); if (fq == 0) SSQ[(size_t)row * 16 + slot] = ss; } }
	v_pk_mul_f32 v[100:101], v[120:121], v[108:109]
	v_pk_mul_f32 v[98:99], v[118:119], v[106:107]
	s_waitcnt lgkmcnt(0)
	v_pk_mul_f32 v[106:107], v[124:125], v[112:113]
	v_pk_mul_f32 v[108:109], v[122:123], v[110:111]
	v_cvt_pk_bf16_f32 v98, v98, v99
	v_cvt_pk_bf16_f32 v99, v100, v101
	v_mul_f32_e32 v110, v133, v133
	v_cvt_pk_bf16_f32 v100, v108, v109
	v_cvt_pk_bf16_f32 v101, v106, v107
	global_store_dwordx4 v[102:103], v[98:101], off
	v_mul_f32_e32 v108, v123, v123
	v_mul_f32_e32 v109, v125, v125
	v_cvt_pk_bf16_f32 v98, v132, v133
	v_cvt_pk_bf16_f32 v99, v134, v135
	v_cvt_pk_bf16_f32 v100, v136, v137
	v_cvt_pk_bf16_f32 v101, v138, v139
	global_store_dwordx4 v[104:105], v[98:101], off
	ds_read_b128 v[100:103], v255 offset:32
	s_nop 0
	ds_read_b128 v[104:107], v255 offset:48
	v_mul_f32_e32 v98, v119, v119
	v_mul_f32_e32 v99, v121, v121
	v_mul_f32_e32 v111, v135, v135
	v_mul_f32_e32 v112, v137, v137
	v_mul_f32_e32 v113, v139, v139
	v_fmac_f32_e32 v98, v118, v118
	v_fmac_f32_e32 v99, v120, v120
	v_fmac_f32_e32 v108, v122, v122
	v_fmac_f32_e32 v109, v124, v124
	v_fmac_f32_e32 v110, v132, v132
	v_fmac_f32_e32 v111, v134, v134
	v_fmac_f32_e32 v112, v136, v136
	v_fmac_f32_e32 v113, v138, v138
	v_add_f32_e32 v98, v98, v99
	v_add_f32_e32 v99, v108, v109
	v_add_f32_e32 v108, v110, v111
	v_add_f32_e32 v109, v112, v113
	v_add_f32_e32 v98, v98, v99
	v_add_f32_e32 v99, v108, v109
	v_add_f32_e32 v98, v98, v99
	ds_bpermute_b32 v99, v142, v98
	s_waitcnt lgkmcnt(0)
	v_add_f32_e32 v98, v98, v99
	ds_bpermute_b32 v99, v143, v98
	s_waitcnt lgkmcnt(0)
	v_pk_mul_f32 v[102:103], v[134:135], v[102:103]
	v_pk_mul_f32 v[100:101], v[132:133], v[100:101]
	s_waitcnt lgkmcnt(0)
	v_pk_mul_f32 v[104:105], v[136:137], v[104:105]
	v_cvt_pk_bf16_f32 v100, v100, v101
	v_cvt_pk_bf16_f32 v101, v102, v103
	v_pk_mul_f32 v[106:107], v[138:139], v[106:107]
	v_cvt_pk_bf16_f32 v102, v104, v105
	v_lshl_add_u64 v[104:105], s[8:9], 0, v[130:131]
	v_cvt_pk_bf16_f32 v103, v106, v107
	global_store_dwordx4 v[104:105], v[100:103], off
	s_and_saveexec_b64 s[36:37], s[4:5]
	s_cbranch_execz .LBB0_2142
	v_lshlrev_b64 v[100:101], 6, v[198:199]
	v_lshl_add_u64 v[100:101], s[10:11], 0, v[100:101]
	v_lshl_add_u64 v[100:101], s[34:35], 2, v[100:101]
	s_waitcnt lgkmcnt(0)
	v_add_f32_e32 v98, v98, v99
	global_store_dword v[100:101], v98, off
.LBB0_2142:
	s_or_b64 exec, exec, s[36:37]
	v_lshlrev_b32_e32 v98, 16, v126
	s_waitcnt lgkmcnt(0)
	v_and_b32_e32 v99, 0xffff0000, v126
	v_lshlrev_b32_e32 v100, 16, v127
	v_and_b32_e32 v101, 0xffff0000, v127
	v_lshlrev_b32_e32 v102, 16, v128
	v_and_b32_e32 v103, 0xffff0000, v128
	v_lshlrev_b32_e32 v104, 16, v129
	v_and_b32_e32 v105, 0xffff0000, v129
	v_pk_fma_f32 v[100:101], v[96:97], v[48:49], v[100:101]
	v_pk_fma_f32 v[98:99], v[94:95], v[46:47], v[98:99]
	v_pk_fma_f32 v[104:105], v[92:93], v[44:45], v[104:105]
	v_pk_fma_f32 v[102:103], v[90:91], v[42:43], v[102:103]
	v_cvt_pk_bf16_f32 v90, v98, v99
	v_cvt_pk_bf16_f32 v91, v100, v101
	v_lshlrev_b64 v[106:107], 10, v[194:195]
	v_cvt_pk_bf16_f32 v92, v102, v103
	v_cvt_pk_bf16_f32 v93, v104, v105
	global_store_dwordx4 v[196:197], v[90:93], off
	ds_read_b128 v[90:93], v255
	s_nop 0
	ds_read_b128 v[94:97], v255 offset:16
	v_lshl_add_u64 v[106:107], v[106:107], 0, v[186:187]
	v_lshlrev_b32_e32 v108, 16, v114
	v_and_b32_e32 v109, 0xffff0000, v114
	v_lshlrev_b32_e32 v110, 16, v115
	v_and_b32_e32 v111, 0xffff0000, v115
	v_lshlrev_b32_e32 v112, 16, v116
	v_and_b32_e32 v113, 0xffff0000, v116
	v_lshlrev_b32_e32 v114, 16, v117
	v_and_b32_e32 v115, 0xffff0000, v117
	v_lshlrev_b64 v[106:107], 1, v[106:107]
	v_pk_fma_f32 v[108:109], v[86:87], v[38:39], v[108:109]
	v_pk_fma_f32 v[114:115], v[84:85], v[36:37], v[114:115]
	v_pk_fma_f32 v[112:113], v[82:83], v[34:35], v[112:113]
	v_lshl_add_u64 v[86:87], s[8:9], 0, v[106:107]
	v_or_b32_e32 v106, 0x100, v106
	v_pk_fma_f32 v[110:111], v[88:89], v[40:41], v[110:111]
	v_lshl_add_u64 v[88:89], s[0:1], 0, v[106:107]
	s_waitcnt lgkmcnt(0)
	v_pk_mul_f32 v[84:85], v[100:101], v[92:93]
	v_pk_mul_f32 v[82:83], v[98:99], v[90:91]
	s_waitcnt lgkmcnt(0)
	v_pk_mul_f32 v[90:91], v[104:105], v[96:97]
	v_pk_mul_f32 v[92:93], v[102:103], v[94:95]
	v_cvt_pk_bf16_f32 v82, v82, v83
	v_cvt_pk_bf16_f32 v83, v84, v85
	v_mul_f32_e32 v94, v109, v109
	v_cvt_pk_bf16_f32 v84, v92, v93
	v_cvt_pk_bf16_f32 v85, v90, v91
	global_store_dwordx4 v[86:87], v[82:85], off
	v_mul_f32_e32 v92, v103, v103
	v_mul_f32_e32 v93, v105, v105
	v_cvt_pk_bf16_f32 v82, v108, v109
	v_cvt_pk_bf16_f32 v83, v110, v111
	v_cvt_pk_bf16_f32 v84, v112, v113
	v_cvt_pk_bf16_f32 v85, v114, v115
	global_store_dwordx4 v[88:89], v[82:85], off
	ds_read_b128 v[84:87], v255 offset:32
	s_nop 0
	ds_read_b128 v[88:91], v255 offset:48
	v_mul_f32_e32 v82, v99, v99
	v_mul_f32_e32 v83, v101, v101
	v_mul_f32_e32 v95, v111, v111
	v_mul_f32_e32 v96, v113, v113
	v_mul_f32_e32 v97, v115, v115
	v_fmac_f32_e32 v82, v98, v98
	v_fmac_f32_e32 v83, v100, v100
	v_fmac_f32_e32 v92, v102, v102
	v_fmac_f32_e32 v93, v104, v104
	v_fmac_f32_e32 v94, v108, v108
	v_fmac_f32_e32 v95, v110, v110
	v_fmac_f32_e32 v96, v112, v112
	v_fmac_f32_e32 v97, v114, v114
	v_add_f32_e32 v82, v82, v83
	v_add_f32_e32 v83, v92, v93
	v_add_f32_e32 v92, v94, v95
	v_add_f32_e32 v93, v96, v97
	v_add_f32_e32 v82, v82, v83
	v_add_f32_e32 v83, v92, v93
	v_add_f32_e32 v82, v82, v83
	ds_bpermute_b32 v83, v142, v82
	s_waitcnt lgkmcnt(0)
	v_add_f32_e32 v82, v82, v83
	ds_bpermute_b32 v83, v143, v82
	s_waitcnt lgkmcnt(0)
	v_pk_mul_f32 v[86:87], v[110:111], v[86:87]
	v_pk_mul_f32 v[84:85], v[108:109], v[84:85]
	s_waitcnt lgkmcnt(0)
	v_pk_mul_f32 v[88:89], v[112:113], v[88:89]
	v_cvt_pk_bf16_f32 v84, v84, v85
	v_cvt_pk_bf16_f32 v85, v86, v87
	v_pk_mul_f32 v[90:91], v[114:115], v[90:91]
	v_cvt_pk_bf16_f32 v86, v88, v89
	v_lshl_add_u64 v[88:89], s[8:9], 0, v[106:107]
	v_cvt_pk_bf16_f32 v87, v90, v91
	global_store_dwordx4 v[88:89], v[84:87], off
	s_and_saveexec_b64 s[36:37], s[4:5]
	s_cbranch_execz .LBB0_2144
	v_lshlrev_b64 v[84:85], 6, v[194:195]
	v_lshl_add_u64 v[84:85], s[10:11], 0, v[84:85]
	v_lshl_add_u64 v[84:85], s[34:35], 2, v[84:85]
	s_waitcnt lgkmcnt(0)
	v_add_f32_e32 v82, v82, v83
	global_store_dword v[84:85], v82, off
; __device__ __forceinline__ void unpack8(const v4u w, float (&o)[8]) { o[0] = bflo(w.x); o[1] = bfhi(w.x); o[2] = bflo(w.y); o[3] = bfhi(w.y); o[4] = bflo(w.z); o[5] = bfhi(w.z); o[6] = bflo(w.w); o[7] = bfhi(w.w); }
; __device__ __forceinline__ unsigned cvt_pk_bf16(float lo, float hi) { unsigned r; asm volatile("v_cvt_pk_bf16_f32 %0, %1, %2" : "=v"(r) : "v"(lo), "v"(hi)); return r; }
;     template <int AI> __device__ __forceinline__ void half_rows(AccT acc, int row0, int col0, int slot, int sq, int fq, const f32x4 (&gsc)[4]) const {
;     ...
;             for (int bj = 0; bj < 2; ++bj) xw[m][bj] = *(const v4u*)(X + (size_t)(row0 + m * 16) * DM + col0 + bj * HALF);
; #pragma unroll
;         for (int m = 0; m < 4; ++m) { const int row = row0 + m * 16;
;             float ss = 0.f;
; #pragma unroll
;             for (int bj = 0; bj < 2; ++bj) { const size_t off = (size_t)row * DM + col0 + bj * HALF;
;                 float xi[8]; unpack8(xw[m][bj], xi);
;                 const f32x4 x0 = (f32x4){xi[0], xi[1], xi[2], xi[3]} + gsc[bj * 2] * acc[AI][bj][m][0], x1 = (f32x4){xi[4], xi[5], xi[6], xi[7]} + gsc[bj * 2 + 1] * acc[AI][bj][m][1];
;                 { u32x4 xs_; xs_.x = cvt_pk_bf16(x0[0], x0[1]); xs_.y = cvt_pk_bf16(x0[2], x0[3]); xs_.z = cvt_pk_bf16(x1[0], x1[1]); xs_.w = cvt_pk_bf16(x1[2], x1[3]); *(u32x4*)(X + off) = xs_; }
;                 if (NEXT) { ss += ((x0.x * x0.x + x0.y * x0.y) + (x0.z * x0.z + x0.w * x0.w)) + ((x1.x * x1.x + x1.y * x1.y) + (x1.z * x1.z + x1.w * x1.w));
;                     const float* gp_ = gam + (size_t)sq * DM + col0 + bj * HALF; const f32x4 y0 = x0 * *(const f32x4*)gp_, y1 = x1 * *(const f32x4*)(gp_ + 4);
;                     u32x4 w; w.x = cvt_pk_bf16(y0[0], y0[1]); w.y = cvt_pk_bf16(y0[2], y0[3]); w.z = cvt_pk_bf16(y1[0], y1[1]); w.w = cvt_pk_bf16(y1[2], y1[3]);
;                     *(u32x4*)(XB + off) = w; } }
;             if (NEXT) { ss += __shfl_xor(ss, 16); ss += __shfl_xor(ss, 32); if (fq == 0) SSQ[(size_t)row * 16 + slot] = ss; } }
.LBB0_2144:
	s_or_b64 exec, exec, s[36:37]
	v_add_u32_e32 v118, 0x80, v192
	v_ashrrev_i32_e32 v119, 31, v118
	s_waitcnt lgkmcnt(0)
	v_lshlrev_b64 v[82:83], 11, v[118:119]
	v_lshl_add_u64 v[128:129], v[190:191], 0, v[82:83]
	global_load_dwordx4 v[120:123], v[128:129], off
	v_add_u32_e32 v114, 0x90, v192
	v_add_u32_e32 v110, 0xa0, v192
	v_add_u32_e32 v106, 0xb0, v192
	v_ashrrev_i32_e32 v115, 31, v114
	v_ashrrev_i32_e32 v111, 31, v110
	v_ashrrev_i32_e32 v107, 31, v106
	v_lshlrev_b64 v[82:83], 11, v[114:115]
	v_lshlrev_b64 v[84:85], 11, v[110:111]
	v_lshlrev_b64 v[86:87], 11, v[106:107]
	v_lshl_add_u64 v[116:117], v[190:191], 0, v[82:83]
	v_lshl_add_u64 v[112:113], v[190:191], 0, v[84:85]
	v_lshl_add_u64 v[108:109], v[190:191], 0, v[86:87]
	global_load_dwordx4 v[124:127], v[128:129], off offset:256
	global_load_dwordx4 v[102:105], v[116:117], off
	global_load_dwordx4 v[98:101], v[116:117], off offset:256
	global_load_dwordx4 v[94:97], v[112:113], off
	global_load_dwordx4 v[90:93], v[112:113], off offset:256
	global_load_dwordx4 v[86:89], v[108:109], off
	global_load_dwordx4 v[82:85], v[108:109], off offset:256
	s_waitcnt vmcnt(0) lgkmcnt(0)
	v_lshlrev_b32_e32 v130, 16, v120
	v_and_b32_e32 v131, 0xffff0000, v120
	v_lshlrev_b32_e32 v120, 16, v121
	v_and_b32_e32 v121, 0xffff0000, v121
	v_lshlrev_b32_e32 v132, 16, v122
	v_and_b32_e32 v133, 0xffff0000, v122
	v_lshlrev_b32_e32 v122, 16, v123
	v_and_b32_e32 v123, 0xffff0000, v123
	v_pk_fma_f32 v[120:121], v[80:81], v[48:49], v[120:121]
	v_pk_fma_f32 v[130:131], v[78:79], v[46:47], v[130:131]
	v_pk_fma_f32 v[122:123], v[76:77], v[44:45], v[122:123]
	v_pk_fma_f32 v[132:133], v[74:75], v[42:43], v[132:133]
	v_cvt_pk_bf16_f32 v74, v130, v131
	v_cvt_pk_bf16_f32 v75, v120, v121
	s_waitcnt lgkmcnt(0)
	v_lshlrev_b32_e32 v140, 16, v126
	v_cvt_pk_bf16_f32 v76, v132, v133
	v_cvt_pk_bf16_f32 v77, v122, v123
	global_store_dwordx4 v[128:129], v[74:77], off
	ds_read_b128 v[74:77], v255
	s_nop 0
	ds_read_b128 v[78:81], v255 offset:16
	v_lshlrev_b64 v[128:129], 10, v[118:119]
	v_lshl_add_u64 v[128:129], v[128:129], 0, v[186:187]
	v_lshlrev_b64 v[128:129], 1, v[128:129]
	v_and_b32_e32 v141, 0xffff0000, v126
	v_lshlrev_b32_e32 v126, 16, v127
	v_and_b32_e32 v127, 0xffff0000, v127
	v_lshl_add_u64 v[134:135], s[8:9], 0, v[128:129]
	v_or_b32_e32 v128, 0x100, v128
	v_lshlrev_b32_e32 v138, 16, v124
	v_and_b32_e32 v139, 0xffff0000, v124
	v_lshlrev_b32_e32 v124, 16, v125
	v_and_b32_e32 v125, 0xffff0000, v125
	v_pk_fma_f32 v[126:127], v[68:69], v[36:37], v[126:127]
	v_pk_fma_f32 v[140:141], v[66:67], v[34:35], v[140:141]
	v_lshl_add_u64 v[136:137], s[0:1], 0, v[128:129]
	v_pk_fma_f32 v[124:125], v[72:73], v[40:41], v[124:125]
	v_pk_fma_f32 v[138:139], v[70:71], v[38:39], v[138:139]
	s_waitcnt lgkmcnt(0)
	v_pk_mul_f32 v[68:69], v[120:121], v[76:77]
	v_pk_mul_f32 v[66:67], v[130:131], v[74:75]
	s_waitcnt lgkmcnt(0)
	v_pk_mul_f32 v[70:71], v[122:123], v[80:81]
	v_pk_mul_f32 v[72:73], v[132:133], v[78:79]
	v_cvt_pk_bf16_f32 v66, v66, v67
	v_cvt_pk_bf16_f32 v67, v68, v69
	v_mul_f32_e32 v76, v133, v133
	v_cvt_pk_bf16_f32 v68, v72, v73
	v_cvt_pk_bf16_f32 v69, v70, v71
	global_store_dwordx4 v[134:135], v[66:69], off
	v_mul_f32_e32 v77, v123, v123
	v_mul_f32_e32 v78, v139, v139
	v_cvt_pk_bf16_f32 v66, v138, v139
	v_cvt_pk_bf16_f32 v67, v124, v125
	v_cvt_pk_bf16_f32 v68, v140, v141
	v_cvt_pk_bf16_f32 v69, v126, v127
	global_store_dwordx4 v[136:137], v[66:69], off
	ds_read_b128 v[68:71], v255 offset:32
	s_nop 0
	ds_read_b128 v[72:75], v255 offset:48
	v_mul_f32_e32 v66, v131, v131
	v_mul_f32_e32 v67, v121, v121
	v_mul_f32_e32 v79, v125, v125
	v_mul_f32_e32 v80, v141, v141
	v_mul_f32_e32 v81, v127, v127
	v_fmac_f32_e32 v66, v130, v130
	v_fmac_f32_e32 v67, v120, v120
	v_fmac_f32_e32 v76, v132, v132
	v_fmac_f32_e32 v77, v122, v122
	v_fmac_f32_e32 v78, v138, v138
	v_fmac_f32_e32 v79, v124, v124
	v_fmac_f32_e32 v80, v140, v140
	v_fmac_f32_e32 v81, v126, v126
	v_add_f32_e32 v66, v66, v67
	v_add_f32_e32 v67, v76, v77
	v_add_f32_e32 v76, v78, v79
	v_add_f32_e32 v77, v80, v81
	v_add_f32_e32 v66, v66, v67
	v_add_f32_e32 v67, v76, v77
	v_add_f32_e32 v66, v66, v67
	ds_bpermute_b32 v67, v142, v66
	s_waitcnt lgkmcnt(0)
	v_add_f32_e32 v66, v66, v67
	ds_bpermute_b32 v67, v143, v66
	s_waitcnt lgkmcnt(0)
	v_pk_mul_f32 v[70:71], v[124:125], v[70:71]
	v_pk_mul_f32 v[68:69], v[138:139], v[68:69]
	s_waitcnt lgkmcnt(0)
	v_pk_mul_f32 v[72:73], v[140:141], v[72:73]
	v_cvt_pk_bf16_f32 v68, v68, v69
	v_cvt_pk_bf16_f32 v69, v70, v71
	v_pk_mul_f32 v[74:75], v[126:127], v[74:75]
	v_cvt_pk_bf16_f32 v70, v72, v73
	v_lshl_add_u64 v[72:73], s[8:9], 0, v[128:129]
	v_cvt_pk_bf16_f32 v71, v74, v75
	global_store_dwordx4 v[72:73], v[68:71], off
	s_and_saveexec_b64 s[36:37], s[4:5]
	s_cbranch_execz .LBB0_2146
	v_lshlrev_b64 v[68:69], 6, v[118:119]
	v_lshl_add_u64 v[68:69], s[10:11], 0, v[68:69]
	v_lshl_add_u64 v[68:69], s[34:35], 2, v[68:69]
	s_waitcnt lgkmcnt(0)
	v_add_f32_e32 v66, v66, v67
	global_store_dword v[68:69], v66, off
; __device__ __forceinline__ void unpack8(const v4u w, float (&o)[8]) { o[0] = bflo(w.x); o[1] = bfhi(w.x); o[2] = bflo(w.y); o[3] = bfhi(w.y); o[4] = bflo(w.z); o[5] = bfhi(w.z); o[6] = bflo(w.w); o[7] = bfhi(w.w); }
; __device__ __forceinline__ unsigned cvt_pk_bf16(float lo, float hi) { unsigned r; asm volatile("v_cvt_pk_bf16_f32 %0, %1, %2" : "=v"(r) : "v"(lo), "v"(hi)); return r; }
;     template <int AI> __device__ __forceinline__ void half_rows(AccT acc, int row0, int col0, int slot, int sq, int fq, const f32x4 (&gsc)[4]) const {
;     ...
;         for (int m = 0; m < 4; ++m) { const int row = row0 + m * 16;
;             float ss = 0.f;
; #pragma unroll
;             for (int bj = 0; bj < 2; ++bj) { const size_t off = (size_t)row * DM + col0 + bj * HALF;
;                 float xi[8]; unpack8(xw[m][bj], xi);
;                 const f32x4 x0 = (f32x4){xi[0], xi[1], xi[2], xi[3]} + gsc[bj * 2] * acc[AI][bj][m][0], x1 = (f32x4){xi[4], xi[5], xi[6], xi[7]} + gsc[bj * 2 + 1] * acc[AI][bj][m][1];
;                 { u32x4 xs_; xs_.x = cvt_pk_bf16(x0[0], x0[1]); xs_.y = cvt_pk_bf16(x0[2], x0[3]); xs_.z = cvt_pk_bf16(x1[0], x1[1]); xs_.w = cvt_pk_bf16(x1[2], x1[3]); *(u32x4*)(X + off) = xs_; }
;                 if (NEXT) { ss += ((x0.x * x0.x + x0.y * x0.y) + (x0.z * x0.z + x0.w * x0.w)) + ((x1.x * x1.x + x1.y * x1.y) + (x1.z * x1.z + x1.w * x1.w));
;                     const float* gp_ = gam + (size_t)sq * DM + col0 + bj * HALF; const f32x4 y0 = x0 * *(const f32x4*)gp_, y1 = x1 * *(const f32x4*)(gp_ + 4);
;                     u32x4 w; w.x = cvt_pk_bf16(y0[0], y0[1]); w.y = cvt_pk_bf16(y0[2], y0[3]); w.z = cvt_pk_bf16(y1[0], y1[1]); w.w = cvt_pk_bf16(y1[2], y1[3]);
;                     *(u32x4*)(XB + off) = w; } }
;             if (NEXT) { ss += __shfl_xor(ss, 16); ss += __shfl_xor(ss, 32); if (fq == 0) SSQ[(size_t)row * 16 + slot] = ss; } }
.LBB0_2146:
	s_or_b64 exec, exec, s[36:37]
	v_lshlrev_b32_e32 v66, 16, v102
	s_waitcnt lgkmcnt(0)
	v_and_b32_e32 v67, 0xffff0000, v102
	v_lshlrev_b32_e32 v68, 16, v103
	v_and_b32_e32 v69, 0xffff0000, v103
	v_lshlrev_b32_e32 v70, 16, v104
	v_and_b32_e32 v71, 0xffff0000, v104
	v_lshlrev_b32_e32 v72, 16, v105
	v_and_b32_e32 v73, 0xffff0000, v105
	v_pk_fma_f32 v[68:69], v[64:65], v[48:49], v[68:69]
	v_pk_fma_f32 v[66:67], v[62:63], v[46:47], v[66:67]
	v_pk_fma_f32 v[72:73], v[60:61], v[44:45], v[72:73]
	v_pk_fma_f32 v[70:71], v[58:59], v[42:43], v[70:71]
	v_cvt_pk_bf16_f32 v58, v66, v67
	v_cvt_pk_bf16_f32 v59, v68, v69
	v_lshlrev_b64 v[74:75], 10, v[114:115]
	v_cvt_pk_bf16_f32 v60, v70, v71
	v_cvt_pk_bf16_f32 v61, v72, v73
	global_store_dwordx4 v[116:117], v[58:61], off
	ds_read_b128 v[58:61], v255
	s_nop 0
	ds_read_b128 v[62:65], v255 offset:16
	v_lshl_add_u64 v[74:75], v[74:75], 0, v[186:187]
	v_lshlrev_b32_e32 v76, 16, v98
	v_and_b32_e32 v77, 0xffff0000, v98
	v_lshlrev_b32_e32 v78, 16, v99
	v_and_b32_e32 v79, 0xffff0000, v99
	v_lshlrev_b32_e32 v80, 16, v100
	v_and_b32_e32 v81, 0xffff0000, v100
	v_lshlrev_b32_e32 v98, 16, v101
	v_and_b32_e32 v99, 0xffff0000, v101
	v_lshlrev_b64 v[74:75], 1, v[74:75]
	v_pk_fma_f32 v[76:77], v[54:55], v[38:39], v[76:77]
	v_pk_fma_f32 v[98:99], v[52:53], v[36:37], v[98:99]
	v_pk_fma_f32 v[80:81], v[50:51], v[34:35], v[80:81]
	v_lshl_add_u64 v[54:55], s[8:9], 0, v[74:75]
	v_or_b32_e32 v74, 0x100, v74
	v_pk_fma_f32 v[78:79], v[56:57], v[40:41], v[78:79]
	v_lshl_add_u64 v[56:57], s[0:1], 0, v[74:75]
	s_waitcnt lgkmcnt(0)
	v_pk_mul_f32 v[52:53], v[68:69], v[60:61]
	v_pk_mul_f32 v[50:51], v[66:67], v[58:59]
	s_waitcnt lgkmcnt(0)
	v_pk_mul_f32 v[58:59], v[72:73], v[64:65]
	v_pk_mul_f32 v[60:61], v[70:71], v[62:63]
	v_cvt_pk_bf16_f32 v50, v50, v51
	v_cvt_pk_bf16_f32 v51, v52, v53
	v_mul_f32_e32 v62, v77, v77
	v_cvt_pk_bf16_f32 v52, v60, v61
	v_cvt_pk_bf16_f32 v53, v58, v59
	global_store_dwordx4 v[54:55], v[50:53], off
	v_mul_f32_e32 v60, v71, v71
	v_mul_f32_e32 v61, v73, v73
	v_cvt_pk_bf16_f32 v50, v76, v77
	v_cvt_pk_bf16_f32 v51, v78, v79
	v_cvt_pk_bf16_f32 v52, v80, v81
	v_cvt_pk_bf16_f32 v53, v98, v99
	global_store_dwordx4 v[56:57], v[50:53], off
	ds_read_b128 v[52:55], v255 offset:32
	s_nop 0
	ds_read_b128 v[56:59], v255 offset:48
	v_mul_f32_e32 v50, v67, v67
	v_mul_f32_e32 v51, v69, v69
	v_mul_f32_e32 v63, v79, v79
	v_mul_f32_e32 v64, v81, v81
	v_mul_f32_e32 v65, v99, v99
	v_fmac_f32_e32 v50, v66, v66
	v_fmac_f32_e32 v51, v68, v68
	v_fmac_f32_e32 v60, v70, v70
	v_fmac_f32_e32 v61, v72, v72
	v_fmac_f32_e32 v62, v76, v76
	v_fmac_f32_e32 v63, v78, v78
	v_fmac_f32_e32 v64, v80, v80
	v_fmac_f32_e32 v65, v98, v98
	v_add_f32_e32 v50, v50, v51
	v_add_f32_e32 v51, v60, v61
	v_add_f32_e32 v60, v62, v63
	v_add_f32_e32 v61, v64, v65
	v_add_f32_e32 v50, v50, v51
	v_add_f32_e32 v51, v60, v61
	v_add_f32_e32 v50, v50, v51
	ds_bpermute_b32 v51, v142, v50
	s_waitcnt lgkmcnt(0)
	v_add_f32_e32 v50, v50, v51
	ds_bpermute_b32 v51, v143, v50
	s_waitcnt lgkmcnt(0)
	v_pk_mul_f32 v[54:55], v[78:79], v[54:55]
	v_pk_mul_f32 v[52:53], v[76:77], v[52:53]
	s_waitcnt lgkmcnt(0)
	v_pk_mul_f32 v[56:57], v[80:81], v[56:57]
	v_cvt_pk_bf16_f32 v52, v52, v53
	v_cvt_pk_bf16_f32 v53, v54, v55
	v_pk_mul_f32 v[58:59], v[98:99], v[58:59]
	v_cvt_pk_bf16_f32 v54, v56, v57
	v_lshl_add_u64 v[56:57], s[8:9], 0, v[74:75]
	v_cvt_pk_bf16_f32 v55, v58, v59
	global_store_dwordx4 v[56:57], v[52:55], off
	s_and_saveexec_b64 s[36:37], s[4:5]
	s_cbranch_execz .LBB0_2148
	v_lshlrev_b64 v[52:53], 6, v[114:115]
	v_lshl_add_u64 v[52:53], s[10:11], 0, v[52:53]
	v_lshl_add_u64 v[52:53], s[34:35], 2, v[52:53]
	s_waitcnt lgkmcnt(0)
	v_add_f32_e32 v50, v50, v51
	global_store_dword v[52:53], v50, off
.LBB0_2148:
	s_or_b64 exec, exec, s[36:37]
	v_lshlrev_b32_e32 v50, 16, v94
	s_waitcnt lgkmcnt(0)
	v_and_b32_e32 v51, 0xffff0000, v94
	v_lshlrev_b32_e32 v52, 16, v95
	v_and_b32_e32 v53, 0xffff0000, v95
	v_lshlrev_b32_e32 v54, 16, v96
	v_and_b32_e32 v55, 0xffff0000, v96
	v_lshlrev_b32_e32 v56, 16, v97
	v_and_b32_e32 v57, 0xffff0000, v97
	v_pk_fma_f32 v[52:53], v[32:33], v[48:49], v[52:53]
	v_pk_fma_f32 v[50:51], v[30:31], v[46:47], v[50:51]
	v_pk_fma_f32 v[56:57], v[28:29], v[44:45], v[56:57]
	v_pk_fma_f32 v[54:55], v[26:27], v[42:43], v[54:55]
	v_cvt_pk_bf16_f32 v26, v50, v51
	v_cvt_pk_bf16_f32 v27, v52, v53
	v_lshlrev_b64 v[58:59], 10, v[110:111]
	v_cvt_pk_bf16_f32 v28, v54, v55
	v_cvt_pk_bf16_f32 v29, v56, v57
	global_store_dwordx4 v[112:113], v[26:29], off
	ds_read_b128 v[26:29], v255
	s_nop 0
	ds_read_b128 v[30:33], v255 offset:16
	v_lshl_add_u64 v[58:59], v[58:59], 0, v[186:187]
	v_lshlrev_b32_e32 v60, 16, v90
	v_and_b32_e32 v61, 0xffff0000, v90
	v_lshlrev_b32_e32 v64, 16, v92
	v_and_b32_e32 v65, 0xffff0000, v92
	v_lshlrev_b32_e32 v66, 16, v93
	v_and_b32_e32 v67, 0xffff0000, v93
	v_lshlrev_b64 v[58:59], 1, v[58:59]
	v_lshlrev_b32_e32 v62, 16, v91
	v_and_b32_e32 v63, 0xffff0000, v91
	v_pk_fma_f32 v[60:61], v[22:23], v[38:39], v[60:61]
	v_pk_fma_f32 v[66:67], v[20:21], v[36:37], v[66:67]
	v_pk_fma_f32 v[64:65], v[18:19], v[34:35], v[64:65]
	v_lshl_add_u64 v[22:23], s[8:9], 0, v[58:59]
	v_or_b32_e32 v58, 0x100, v58
	v_pk_fma_f32 v[62:63], v[24:25], v[40:41], v[62:63]
	v_lshl_add_u64 v[24:25], s[0:1], 0, v[58:59]
	s_waitcnt lgkmcnt(0)
	v_pk_mul_f32 v[20:21], v[52:53], v[28:29]
	v_pk_mul_f32 v[18:19], v[50:51], v[26:27]
	s_waitcnt lgkmcnt(0)
; __device__ __forceinline__ void unpack8(const v4u w, float (&o)[8]) { o[0] = bflo(w.x); o[1] = bfhi(w.x); o[2] = bflo(w.y); o[3] = bfhi(w.y); o[4] = bflo(w.z); o[5] = bfhi(w.z); o[6] = bflo(w.w); o[7] = bfhi(w.w); }
; __device__ __forceinline__ unsigned cvt_pk_bf16(float lo, float hi) { unsigned r; asm volatile("v_cvt_pk_bf16_f32 %0, %1, %2" : "=v"(r) : "v"(lo), "v"(hi)); return r; }
;     template <int AI> __device__ __forceinline__ void half_rows(AccT acc, int row0, int col0, int slot, int sq, int fq, const f32x4 (&gsc)[4]) const {
;     ...
;         for (int m = 0; m < 4; ++m) { const int row = row0 + m * 16;
;             float ss = 0.f;
; #pragma unroll
;             for (int bj = 0; bj < 2; ++bj) { const size_t off = (size_t)row * DM + col0 + bj * HALF;
;                 float xi[8]; unpack8(xw[m][bj], xi);
;                 const f32x4 x0 = (f32x4){xi[0], xi[1], xi[2], xi[3]} + gsc[bj * 2] * acc[AI][bj][m][0], x1 = (f32x4){xi[4], xi[5], xi[6], xi[7]} + gsc[bj * 2 + 1] * acc[AI][bj][m][1];
;                 { u32x4 xs_; xs_.x = cvt_pk_bf16(x0[0], x0[1]); xs_.y = cvt_pk_bf16(x0[2], x0[3]); xs_.z = cvt_pk_bf16(x1[0], x1[1]); xs_.w = cvt_pk_bf16(x1[2], x1[3]); *(u32x4*)(X + off) = xs_; }
;                 if (NEXT) { ss += ((x0.x * x0.x + x0.y * x0.y) + (x0.z * x0.z + x0.w * x0.w)) + ((x1.x * x1.x + x1.y * x1.y) + (x1.z * x1.z + x1.w * x1.w));
;                     const float* gp_ = gam + (size_t)sq * DM + col0 + bj * HALF; const f32x4 y0 = x0 * *(const f32x4*)gp_, y1 = x1 * *(const f32x4*)(gp_ + 4);
;                     u32x4 w; w.x = cvt_pk_bf16(y0[0], y0[1]); w.y = cvt_pk_bf16(y0[2], y0[3]); w.z = cvt_pk_bf16(y1[0], y1[1]); w.w = cvt_pk_bf16(y1[2], y1[3]);
;                     *(u32x4*)(XB + off) = w; } }
;             if (NEXT) { ss += __shfl_xor(ss, 16); ss += __shfl_xor(ss, 32); if (fq == 0) SSQ[(size_t)row * 16 + slot] = ss; } }
	v_pk_mul_f32 v[26:27], v[56:57], v[32:33]
	v_pk_mul_f32 v[28:29], v[54:55], v[30:31]
	v_cvt_pk_bf16_f32 v18, v18, v19
	v_cvt_pk_bf16_f32 v19, v20, v21
	v_mul_f32_e32 v30, v61, v61
	v_cvt_pk_bf16_f32 v20, v28, v29
	v_cvt_pk_bf16_f32 v21, v26, v27
	global_store_dwordx4 v[22:23], v[18:21], off
	v_mul_f32_e32 v28, v55, v55
	v_mul_f32_e32 v29, v57, v57
	v_cvt_pk_bf16_f32 v18, v60, v61
	v_cvt_pk_bf16_f32 v19, v62, v63
	v_cvt_pk_bf16_f32 v20, v64, v65
	v_cvt_pk_bf16_f32 v21, v66, v67
	global_store_dwordx4 v[24:25], v[18:21], off
	ds_read_b128 v[20:23], v255 offset:32
	s_nop 0
	ds_read_b128 v[24:27], v255 offset:48
	v_mul_f32_e32 v18, v51, v51
	v_mul_f32_e32 v19, v53, v53
	v_mul_f32_e32 v31, v63, v63
	v_mul_f32_e32 v32, v65, v65
	v_mul_f32_e32 v33, v67, v67
	v_fmac_f32_e32 v18, v50, v50
	v_fmac_f32_e32 v19, v52, v52
	v_fmac_f32_e32 v28, v54, v54
	v_fmac_f32_e32 v29, v56, v56
	v_fmac_f32_e32 v30, v60, v60
	v_fmac_f32_e32 v31, v62, v62
	v_fmac_f32_e32 v32, v64, v64
	v_fmac_f32_e32 v33, v66, v66
	v_add_f32_e32 v18, v18, v19
	v_add_f32_e32 v19, v28, v29
	v_add_f32_e32 v28, v30, v31
	v_add_f32_e32 v29, v32, v33
	v_add_f32_e32 v18, v18, v19
	v_add_f32_e32 v19, v28, v29
	v_add_f32_e32 v18, v18, v19
	ds_bpermute_b32 v19, v142, v18
	s_waitcnt lgkmcnt(0)
	v_add_f32_e32 v18, v18, v19
	ds_bpermute_b32 v19, v143, v18
	s_waitcnt lgkmcnt(0)
	v_pk_mul_f32 v[22:23], v[62:63], v[22:23]
	v_pk_mul_f32 v[20:21], v[60:61], v[20:21]
	s_waitcnt lgkmcnt(0)
	v_pk_mul_f32 v[24:25], v[64:65], v[24:25]
	v_cvt_pk_bf16_f32 v20, v20, v21
	v_cvt_pk_bf16_f32 v21, v22, v23
	v_pk_mul_f32 v[26:27], v[66:67], v[26:27]
	v_cvt_pk_bf16_f32 v22, v24, v25
	v_lshl_add_u64 v[24:25], s[8:9], 0, v[58:59]
	v_cvt_pk_bf16_f32 v23, v26, v27
	global_store_dwordx4 v[24:25], v[20:23], off
	s_and_saveexec_b64 s[36:37], s[4:5]
	s_cbranch_execz .LBB0_2150
	v_lshlrev_b64 v[20:21], 6, v[110:111]
	v_lshl_add_u64 v[20:21], s[10:11], 0, v[20:21]
	v_lshl_add_u64 v[20:21], s[34:35], 2, v[20:21]
	s_waitcnt lgkmcnt(0)
	v_add_f32_e32 v18, v18, v19
	global_store_dword v[20:21], v18, off
.LBB0_2150:
	s_or_b64 exec, exec, s[36:37]
	v_lshlrev_b32_e32 v18, 16, v86
	s_waitcnt lgkmcnt(0)
	v_and_b32_e32 v19, 0xffff0000, v86
	v_lshlrev_b32_e32 v20, 16, v87
	v_and_b32_e32 v21, 0xffff0000, v87
	v_lshlrev_b32_e32 v22, 16, v88
	v_and_b32_e32 v23, 0xffff0000, v88
	v_lshlrev_b32_e32 v24, 16, v89
	v_and_b32_e32 v25, 0xffff0000, v89
	v_pk_fma_f32 v[20:21], v[16:17], v[48:49], v[20:21]
	v_pk_fma_f32 v[18:19], v[14:15], v[46:47], v[18:19]
	v_pk_fma_f32 v[24:25], v[12:13], v[44:45], v[24:25]
	v_pk_fma_f32 v[22:23], v[10:11], v[42:43], v[22:23]
	v_cvt_pk_bf16_f32 v10, v18, v19
	v_cvt_pk_bf16_f32 v11, v20, v21
	v_lshlrev_b64 v[26:27], 10, v[106:107]
	v_cvt_pk_bf16_f32 v12, v22, v23
	v_cvt_pk_bf16_f32 v13, v24, v25
	global_store_dwordx4 v[108:109], v[10:13], off
	ds_read_b128 v[10:13], v255
	s_nop 0
	ds_read_b128 v[14:17], v255 offset:16
	v_lshl_add_u64 v[26:27], v[26:27], 0, v[186:187]
	v_lshlrev_b32_e32 v28, 16, v82
	v_and_b32_e32 v29, 0xffff0000, v82
	v_lshlrev_b32_e32 v32, 16, v84
	v_and_b32_e32 v33, 0xffff0000, v84
	v_lshlrev_b32_e32 v42, 16, v85
	v_and_b32_e32 v43, 0xffff0000, v85
	v_lshlrev_b64 v[26:27], 1, v[26:27]
	v_lshlrev_b32_e32 v30, 16, v83
	v_and_b32_e32 v31, 0xffff0000, v83
	v_pk_fma_f32 v[28:29], v[6:7], v[38:39], v[28:29]
	v_pk_fma_f32 v[36:37], v[4:5], v[36:37], v[42:43]
	v_pk_fma_f32 v[32:33], v[2:3], v[34:35], v[32:33]
	v_lshl_add_u64 v[6:7], s[8:9], 0, v[26:27]
	v_or_b32_e32 v26, 0x100, v26
	v_pk_fma_f32 v[30:31], v[8:9], v[40:41], v[30:31]
	v_lshl_add_u64 v[8:9], s[0:1], 0, v[26:27]
	s_waitcnt lgkmcnt(0)
	v_pk_mul_f32 v[4:5], v[20:21], v[12:13]
	v_pk_mul_f32 v[2:3], v[18:19], v[10:11]
	s_waitcnt lgkmcnt(0)
	v_pk_mul_f32 v[10:11], v[24:25], v[16:17]
	v_pk_mul_f32 v[12:13], v[22:23], v[14:15]
	v_cvt_pk_bf16_f32 v2, v2, v3
	v_cvt_pk_bf16_f32 v3, v4, v5
	v_mul_f32_e32 v14, v29, v29
	v_cvt_pk_bf16_f32 v4, v12, v13
	v_cvt_pk_bf16_f32 v5, v10, v11
	global_store_dwordx4 v[6:7], v[2:5], off
	v_mul_f32_e32 v12, v23, v23
	v_mul_f32_e32 v13, v25, v25
	v_cvt_pk_bf16_f32 v2, v28, v29
	v_cvt_pk_bf16_f32 v3, v30, v31
	v_cvt_pk_bf16_f32 v4, v32, v33
	v_cvt_pk_bf16_f32 v5, v36, v37
	global_store_dwordx4 v[8:9], v[2:5], off
	ds_read_b128 v[4:7], v255 offset:32
	s_nop 0
	ds_read_b128 v[8:11], v255 offset:48
	v_mul_f32_e32 v2, v19, v19
	v_mul_f32_e32 v3, v21, v21
	v_mul_f32_e32 v15, v31, v31
	v_mul_f32_e32 v16, v33, v33
	v_mul_f32_e32 v17, v37, v37
	v_fmac_f32_e32 v2, v18, v18
	v_fmac_f32_e32 v3, v20, v20
	v_fmac_f32_e32 v12, v22, v22
	v_fmac_f32_e32 v13, v24, v24
	v_fmac_f32_e32 v14, v28, v28
	v_fmac_f32_e32 v15, v30, v30
	v_fmac_f32_e32 v16, v32, v32
	v_fmac_f32_e32 v17, v36, v36
	v_add_f32_e32 v2, v2, v3
	v_add_f32_e32 v3, v12, v13
	v_add_f32_e32 v12, v14, v15
	v_add_f32_e32 v13, v16, v17
	v_add_f32_e32 v2, v2, v3
	v_add_f32_e32 v3, v12, v13
	v_add_f32_e32 v2, v2, v3
	ds_bpermute_b32 v3, v142, v2
	s_waitcnt lgkmcnt(0)
	v_add_f32_e32 v2, v2, v3
	ds_bpermute_b32 v3, v143, v2
	s_waitcnt lgkmcnt(0)
	v_pk_mul_f32 v[6:7], v[30:31], v[6:7]
	v_pk_mul_f32 v[4:5], v[28:29], v[4:5]
	s_waitcnt lgkmcnt(0)
	v_pk_mul_f32 v[8:9], v[32:33], v[8:9]
	v_cvt_pk_bf16_f32 v4, v4, v5
	v_cvt_pk_bf16_f32 v5, v6, v7
	v_pk_mul_f32 v[10:11], v[36:37], v[10:11]
	v_cvt_pk_bf16_f32 v6, v8, v9
	v_lshl_add_u64 v[8:9], s[8:9], 0, v[26:27]
	v_cvt_pk_bf16_f32 v7, v10, v11
	global_store_dwordx4 v[8:9], v[4:7], off
	s_and_saveexec_b64 s[36:37], s[4:5]
	s_cbranch_execz .LBB0_2152
	v_lshlrev_b64 v[4:5], 6, v[106:107]
	v_lshl_add_u64 v[4:5], s[10:11], 0, v[4:5]
	v_lshl_add_u64 v[4:5], s[34:35], 2, v[4:5]
	s_waitcnt lgkmcnt(0)
	v_add_f32_e32 v2, v2, v3
	global_store_dword v[4:5], v2, off

; #define LAS __attribute__((address_space(3)))
; __global__ void __launch_bounds__(NWAVES * 64, 2) fwd(Args args_unused) {
;     extern __shared__ __attribute__((aligned(16))) unsigned char lds_raw[];
;     LAS unsigned char* const lds0 = (LAS unsigned char*)lds_raw;
;     volatile LAS unsigned* MISC = (volatile LAS unsigned*)(lds0 + MISC_OFF);
	.amdhsa_kernel _Z3fwd4Args
		.amdhsa_group_segment_fixed_size 0
		.amdhsa_private_segment_fixed_size 0
		.amdhsa_kernarg_size 616
		.amdhsa_user_sgpr_count 2
		.amdhsa_user_sgpr_dispatch_ptr 0
		.amdhsa_user_sgpr_queue_ptr 0
		.amdhsa_user_sgpr_kernarg_segment_ptr 1
		.amdhsa_user_sgpr_dispatch_id 0
		.amdhsa_user_sgpr_kernarg_preload_length 0
		.amdhsa_user_sgpr_kernarg_preload_offset 0
		.amdhsa_user_sgpr_private_segment_size 0
		.amdhsa_uses_dynamic_stack 0
		.amdhsa_enable_private_segment 0
		.amdhsa_system_sgpr_workgroup_id_x 1
		.amdhsa_system_sgpr_workgroup_id_y 0
		.amdhsa_system_sgpr_workgroup_id_z 0
		.amdhsa_system_sgpr_workgroup_info 0
		.amdhsa_system_vgpr_workitem_id 0
		.amdhsa_next_free_vgpr 256
		.amdhsa_next_free_sgpr 98
		.amdhsa_accum_offset 256
		.amdhsa_reserve_vcc 1
		.amdhsa_float_round_mode_32 0
		.amdhsa_float_round_mode_16_64 0
		.amdhsa_float_denorm_mode_32 3
		.amdhsa_float_denorm_mode_16_64 3
		.amdhsa_dx10_clamp 1
		.amdhsa_ieee_mode 1
		.amdhsa_fp16_overflow 0
		.amdhsa_tg_split 0
		.amdhsa_exception_fp_ieee_invalid_op 0
		.amdhsa_exception_fp_denorm_src 0
		.amdhsa_exception_fp_ieee_div_zero 0
		.amdhsa_exception_fp_ieee_overflow 0
		.amdhsa_exception_fp_ieee_underflow 0
		.amdhsa_exception_fp_ieee_inexact 0
		.amdhsa_exception_int_div_zero 0
	.end_amdhsa_kernel
